# nt also on the read-once residual / gate-input loads of the out-proj, down-proj and PLE-gate epilogues
# baseline (speedup 1.0000x reference)
; __device__ __forceinline__ unsigned cvt_pk(float lo, float hi) { unsigned r; asm("v_cvt_pk_bf16_f32 %0, %1, %2" : "=v"(r) : "v"(lo), "v"(hi)); return r; }
;     __device__ __forceinline__ void operator()(AccRef acc, const pg8::Unit& u, int wr, int wc, int, int) const {
;     ...
;                 v4u pw[4][2];
; #pragma unroll
;                 for (int m = 0; m < 4; ++m) { const int row = u.pm * 256 + ai * 128 + wr * 64 + m * 16 + fr;
; #pragma unroll
;                     for (int bj = 0; bj < 2; ++bj) pw[m][bj] = *(const v4u*)(RB + (size_t)row * DM + u.pn * 256 + bj * 128 + wc * 32 + 8 * fq); }
; #pragma unroll
;                 for (int m = 0; m < 4; ++m)
; #pragma unroll
;                     for (int bj = 0; bj < 2; ++bj) { const v4u w = pw[m][bj]; r0[m][bj] = (f32x4){bf_lo(w.x), bf_hi(w.x), bf_lo(w.y), bf_hi(w.y)}; r1[m][bj] = (f32x4){bf_lo(w.z), bf_hi(w.z), bf_lo(w.w), bf_hi(w.w)}; }
;             }
;             asm volatile("" ::: "memory");
; #pragma unroll
;             for (int m = 0; m < 4; ++m) {
;                 const int row = u.pm * 256 + ai * 128 + wr * 64 + m * 16 + fr;
;                 float ss = 0.f;
; #pragma unroll
;                 for (int bj = 0; bj < 2; ++bj) {
;                     const int c0 = u.pn * 256 + bj * 128 + wc * 32 + 8 * fq;
;                     const f32x4 o0 = r0[m][bj] + acc[ai][bj][m][0], o1 = r1[m][bj] + acc[ai][bj][m][1];
;                     v4u w; w.x = cvt_pk(o0[0], o0[1]); w.y = cvt_pk(o0[2], o0[3]); w.z = cvt_pk(o1[0], o1[1]); w.w = cvt_pk(o1[2], o1[3]);
;                     *(v4u*)(HB + (size_t)row * DM + c0) = w;
;                     ss += (o0[0] * o0[0] + o0[1] * o0[1]) + (o0[2] * o0[2] + o0[3] * o0[3]) + (o1[0] * o1[0] + o1[1] * o1[1]) + (o1[2] * o1[2] + o1[3] * o1[3]);
;                 }
;                 if (ssq_off >= 0) { ss += __shfl_xor(ss, 16); ss += __shfl_xor(ss, 32); if (fq == 0) __hip_atomic_fetch_add(ssq + row, ss, __ATOMIC_RELAXED, __HIP_MEMORY_SCOPE_AGENT); }
.LBB0_459:
	s_mov_b64 s[36:37], s[44:45]
	s_mov_b64 s[38:39], s[46:47]
	s_add_u32 s58, s36, 0x7800000
	s_addc_u32 s59, s37, 0
	s_add_u32 s56, s36, 0x22000
	v_mov_b32_e32 v130, v196
	s_addc_u32 s57, s37, 0
	s_lshl_b32 s15, s76, 8
	s_lshl_b32 s38, s66, 8
	s_add_i32 s15, s15, s35
	v_ashrrev_i32_e32 v128, 1, v130
	s_ashr_i32 s39, s38, 31
	v_and_or_b32 v166, v130, 15, s15
	v_and_b32_e32 v128, -8, v128
	s_or_b32 s15, s38, s28
	s_lshl_b64 s[38:39], s[38:39], 1
	v_add_u32_e32 v164, s15, v128
	s_add_u32 s15, s36, s38
	s_addc_u32 s31, s37, s39
	s_add_u32 s36, s15, s70
	s_addc_u32 s37, s31, 0
	v_ashrrev_i32_e32 v129, 31, v128
	v_lshl_add_u64 v[128:129], v[128:129], 1, s[36:37]
	s_mov_b64 s[36:37], 0x3600000
	v_ashrrev_i32_e32 v167, 31, v166
	v_lshl_add_u64 v[168:169], v[128:129], 0, s[36:37]
	v_lshlrev_b64 v[200:201], 11, v[166:167]
	v_lshl_add_u64 v[128:129], v[168:169], 0, v[200:201]
	global_load_dwordx4 v[188:191], v[128:129], off nt
	global_load_dwordx4 v[192:195], v[128:129], off offset:256 nt
	v_or_b32_e32 v176, 16, v166
	v_ashrrev_i32_e32 v177, 31, v176
	v_or_b32_e32 v172, 32, v166
	v_lshlrev_b64 v[180:181], 11, v[176:177]
	v_ashrrev_i32_e32 v173, 31, v172
	v_or_b32_e32 v170, 48, v166
	v_lshl_add_u64 v[128:129], v[168:169], 0, v[180:181]
	v_lshlrev_b64 v[178:179], 11, v[172:173]
	v_ashrrev_i32_e32 v171, 31, v170
	global_load_dwordx4 v[148:151], v[128:129], off nt
	global_load_dwordx4 v[144:147], v[128:129], off offset:256 nt
	v_lshl_add_u64 v[128:129], v[168:169], 0, v[178:179]
	v_lshlrev_b64 v[174:175], 11, v[170:171]
	global_load_dwordx4 v[140:143], v[128:129], off nt
	global_load_dwordx4 v[136:139], v[128:129], off offset:256 nt
	v_lshl_add_u64 v[128:129], v[168:169], 0, v[174:175]
	v_cmp_gt_u32_e32 vcc, 16, v130
	global_load_dwordx4 v[132:135], v[128:129], off nt
	s_nop 0
	global_load_dwordx4 v[128:131], v[128:129], off offset:256 nt
	v_ashrrev_i32_e32 v165, 31, v164
	v_lshl_add_u64 v[200:201], s[58:59], 0, v[200:201]
	v_lshl_add_u64 v[200:201], v[164:165], 1, v[200:201]
	s_waitcnt vmcnt(0)
	v_lshlrev_b32_e32 v202, 16, v188
	v_and_b32_e32 v203, 0xffff0000, v188
	v_lshlrev_b32_e32 v188, 16, v189
	v_and_b32_e32 v189, 0xffff0000, v189
	v_lshlrev_b32_e32 v204, 16, v190
	v_and_b32_e32 v205, 0xffff0000, v190
	v_lshlrev_b32_e32 v190, 16, v191
	v_and_b32_e32 v191, 0xffff0000, v191
	v_lshlrev_b32_e32 v206, 16, v192
	v_and_b32_e32 v207, 0xffff0000, v192
	v_lshlrev_b32_e32 v192, 16, v193
	v_and_b32_e32 v193, 0xffff0000, v193
	v_lshlrev_b32_e32 v208, 16, v194
	v_and_b32_e32 v209, 0xffff0000, v194
	v_lshlrev_b32_e32 v194, 16, v195
	v_and_b32_e32 v195, 0xffff0000, v195
	v_pk_add_f32 v[126:127], v[126:127], v[188:189]
	v_pk_add_f32 v[124:125], v[124:125], v[202:203]
	v_pk_add_f32 v[188:189], v[122:123], v[190:191]
	v_pk_add_f32 v[190:191], v[120:121], v[204:205]
	v_cvt_pk_bf16_f32 v120, v124, v125
	v_cvt_pk_bf16_f32 v121, v126, v127
	v_cvt_pk_bf16_f32 v123, v188, v189
	v_pk_add_f32 v[118:119], v[118:119], v[192:193]
	v_cvt_pk_bf16_f32 v122, v190, v191
	global_store_dwordx4 v[200:201], v[120:123], off
	v_pk_add_f32 v[116:117], v[116:117], v[206:207]
	s_nop 0
	v_pk_add_f32 v[120:121], v[114:115], v[194:195]
	v_pk_add_f32 v[122:123], v[112:113], v[208:209]
	v_cvt_pk_bf16_f32 v113, v118, v119
	v_cvt_pk_bf16_f32 v112, v116, v117
	v_cvt_pk_bf16_f32 v115, v120, v121
	s_nop 0
	v_cvt_pk_bf16_f32 v114, v122, v123
	global_store_dwordx4 v[200:201], v[112:115], off offset:256
	s_nop 1
	v_mul_f32_e32 v113, v125, v125
	v_mul_f32_e32 v114, v127, v127
	v_fmac_f32_e32 v113, v124, v124
	v_fmac_f32_e32 v114, v126, v126
	v_add_f32_e32 v113, v113, v114
	v_mul_f32_e32 v114, v191, v191
	v_fmac_f32_e32 v114, v190, v190
	v_add_f32_e32 v113, v114, v113
	v_mul_f32_e32 v114, v117, v117
	v_mul_f32_e32 v115, v119, v119
	v_mul_f32_e32 v112, v189, v189
	v_fmac_f32_e32 v114, v116, v116
	v_fmac_f32_e32 v115, v118, v118
	v_fmac_f32_e32 v112, v188, v188
	v_add_f32_e32 v114, v114, v115
	v_mul_f32_e32 v115, v123, v123
	v_add_f32_e32 v112, v112, v113
	v_mul_f32_e32 v113, v121, v121
	v_fmac_f32_e32 v115, v122, v122
	v_fmac_f32_e32 v113, v120, v120
	v_add_f32_e32 v114, v115, v114
	v_add_f32_e32 v113, v113, v114
	v_add_f32_e32 v112, v112, v113
	ds_bpermute_b32 v113, v197, v112
	s_waitcnt lgkmcnt(0)
	v_add_f32_e32 v112, v112, v113
	ds_bpermute_b32 v113, v198, v112
	s_and_saveexec_b64 s[66:67], vcc
	s_cbranch_execz .LBB0_461
	s_waitcnt lgkmcnt(0)
	v_add_f32_e32 v114, v112, v113
	v_lshl_add_u64 v[112:113], v[166:167], 2, s[56:57]
	global_atomic_add_f32 v[112:113], v114, off

; __device__ __forceinline__ unsigned cvt_pk(float lo, float hi) { unsigned r; asm("v_cvt_pk_bf16_f32 %0, %1, %2" : "=v"(r) : "v"(lo), "v"(hi)); return r; }
;     __device__ __forceinline__ void operator()(AccRef acc, const pg8::Unit& u, int wr, int wc, int, int) const {
;     ...
;                 for (int m = 0; m < 4; ++m) { const int row = u.pm * 256 + ai * 128 + wr * 64 + m * 16 + fr;
; #pragma unroll
;                     for (int bj = 0; bj < 2; ++bj) pw[m][bj] = *(const v4u*)(RB + (size_t)row * DM + u.pn * 256 + bj * 128 + wc * 32 + 8 * fq); }
; #pragma unroll
;                 for (int m = 0; m < 4; ++m)
; #pragma unroll
;                     for (int bj = 0; bj < 2; ++bj) { const v4u w = pw[m][bj]; r0[m][bj] = (f32x4){bf_lo(w.x), bf_hi(w.x), bf_lo(w.y), bf_hi(w.y)}; r1[m][bj] = (f32x4){bf_lo(w.z), bf_hi(w.z), bf_lo(w.w), bf_hi(w.w)}; }
;             }
;             asm volatile("" ::: "memory");
; #pragma unroll
;             for (int m = 0; m < 4; ++m) {
;                 const int row = u.pm * 256 + ai * 128 + wr * 64 + m * 16 + fr;
;                 float ss = 0.f;
; #pragma unroll
;                 for (int bj = 0; bj < 2; ++bj) {
;                     const int c0 = u.pn * 256 + bj * 128 + wc * 32 + 8 * fq;
;                     const f32x4 o0 = r0[m][bj] + acc[ai][bj][m][0], o1 = r1[m][bj] + acc[ai][bj][m][1];
;                     v4u w; w.x = cvt_pk(o0[0], o0[1]); w.y = cvt_pk(o0[2], o0[3]); w.z = cvt_pk(o1[0], o1[1]); w.w = cvt_pk(o1[2], o1[3]);
;                     *(v4u*)(HB + (size_t)row * DM + c0) = w;
;                     ss += (o0[0] * o0[0] + o0[1] * o0[1]) + (o0[2] * o0[2] + o0[3] * o0[3]) + (o1[0] * o1[0] + o1[1] * o1[1]) + (o1[2] * o1[2] + o1[3] * o1[3]);
;                 }
;                 if (ssq_off >= 0) { ss += __shfl_xor(ss, 16); ss += __shfl_xor(ss, 32); if (fq == 0) __hip_atomic_fetch_add(ssq + row, ss, __ATOMIC_RELAXED, __HIP_MEMORY_SCOPE_AGENT); }
.LBB0_467:
	s_or_b64 exec, exec, s[66:67]
	v_add_u32_e32 v98, 0x80, v166
	v_ashrrev_i32_e32 v99, 31, v98
	v_lshlrev_b64 v[110:111], 11, v[98:99]
	s_waitcnt lgkmcnt(0)
	v_lshl_add_u64 v[64:65], v[168:169], 0, v[110:111]
	global_load_dwordx4 v[102:105], v[64:65], off nt
	global_load_dwordx4 v[106:109], v[64:65], off offset:256 nt
	v_add_u32_e32 v94, 0x90, v166
	v_add_u32_e32 v92, 0xa0, v166
	v_add_u32_e32 v88, 0xb0, v166
	v_ashrrev_i32_e32 v95, 31, v94
	v_ashrrev_i32_e32 v93, 31, v92
	v_ashrrev_i32_e32 v89, 31, v88
	v_lshlrev_b64 v[100:101], 11, v[94:95]
	v_lshlrev_b64 v[96:97], 11, v[92:93]
	v_lshlrev_b64 v[90:91], 11, v[88:89]
	v_lshl_add_u64 v[64:65], v[168:169], 0, v[100:101]
	v_lshl_add_u64 v[66:67], v[168:169], 0, v[96:97]
	v_lshl_add_u64 v[112:113], v[168:169], 0, v[90:91]
	global_load_dwordx4 v[84:87], v[64:65], off nt
	global_load_dwordx4 v[80:83], v[64:65], off offset:256 nt
	global_load_dwordx4 v[76:79], v[66:67], off nt
	global_load_dwordx4 v[72:75], v[66:67], off offset:256 nt
	global_load_dwordx4 v[68:71], v[112:113], off nt
	s_nop 0
	global_load_dwordx4 v[64:67], v[112:113], off offset:256 nt
	v_lshl_add_u64 v[110:111], s[58:59], 0, v[110:111]
	s_waitcnt vmcnt(7)
	v_lshlrev_b32_e32 v112, 16, v102
	v_and_b32_e32 v113, 0xffff0000, v102
	v_lshlrev_b32_e32 v102, 16, v103
	v_and_b32_e32 v103, 0xffff0000, v103
	s_waitcnt vmcnt(6)
	v_lshlrev_b32_e32 v116, 16, v106
	v_and_b32_e32 v117, 0xffff0000, v106
	v_lshlrev_b32_e32 v106, 16, v107
	v_and_b32_e32 v107, 0xffff0000, v107
	v_lshlrev_b32_e32 v114, 16, v104
	v_and_b32_e32 v115, 0xffff0000, v104
	v_lshlrev_b32_e32 v104, 16, v105
	v_and_b32_e32 v105, 0xffff0000, v105
	v_lshlrev_b32_e32 v118, 16, v108
	v_and_b32_e32 v119, 0xffff0000, v108
	v_lshlrev_b32_e32 v108, 16, v109
	v_and_b32_e32 v109, 0xffff0000, v109
	v_pk_add_f32 v[62:63], v[62:63], v[102:103]
	v_pk_add_f32 v[60:61], v[60:61], v[112:113]
	v_pk_add_f32 v[54:55], v[54:55], v[106:107]
	v_pk_add_f32 v[52:53], v[52:53], v[116:117]
	v_pk_add_f32 v[58:59], v[58:59], v[104:105]
	v_pk_add_f32 v[56:57], v[56:57], v[114:115]
	v_pk_add_f32 v[102:103], v[50:51], v[108:109]
	v_pk_add_f32 v[104:105], v[48:49], v[118:119]
	v_cvt_pk_bf16_f32 v48, v60, v61
	v_cvt_pk_bf16_f32 v49, v62, v63
	v_mul_f32_e32 v61, v61, v61
	v_mul_f32_e32 v63, v63, v63
	v_mul_f32_e32 v107, v53, v53
	v_mul_f32_e32 v108, v55, v55
	v_cvt_pk_bf16_f32 v50, v56, v57
	v_mul_f32_e32 v57, v57, v57
	v_mul_f32_e32 v109, v105, v105
	v_fmac_f32_e32 v61, v60, v60
	v_fmac_f32_e32 v63, v62, v62
	v_fmac_f32_e32 v107, v52, v52
	v_fmac_f32_e32 v108, v54, v54
	v_mul_f32_e32 v51, v59, v59
	v_mul_f32_e32 v106, v103, v103
	v_fmac_f32_e32 v57, v56, v56
	v_fmac_f32_e32 v109, v104, v104
	v_add_f32_e32 v56, v61, v63
	v_add_f32_e32 v60, v107, v108
	v_fmac_f32_e32 v51, v58, v58
	v_fmac_f32_e32 v106, v102, v102
	v_add_f32_e32 v56, v57, v56
	v_add_f32_e32 v57, v109, v60
	v_add_f32_e32 v51, v51, v56
	v_add_f32_e32 v56, v106, v57
	v_add_f32_e32 v60, v51, v56
	ds_bpermute_b32 v61, v197, v60
	v_lshl_add_u64 v[56:57], v[164:165], 1, v[110:111]
	v_cvt_pk_bf16_f32 v51, v58, v59
	global_store_dwordx4 v[56:57], v[48:51], off
	s_waitcnt lgkmcnt(0)
	s_nop 0
	v_add_f32_e32 v48, v60, v61
	ds_bpermute_b32 v49, v198, v48
	v_cvt_pk_bf16_f32 v50, v52, v53
	v_cvt_pk_bf16_f32 v51, v54, v55
	v_cvt_pk_bf16_f32 v52, v104, v105
	v_cvt_pk_bf16_f32 v53, v102, v103
	global_store_dwordx4 v[56:57], v[50:53], off offset:256
	s_and_saveexec_b64 s[66:67], vcc
	s_cbranch_execz .LBB0_469
	s_waitcnt lgkmcnt(0)
	v_add_f32_e32 v50, v48, v49
	v_lshl_add_u64 v[48:49], v[98:99], 2, s[56:57]
	global_atomic_add_f32 v[48:49], v50, off

; __device__ __forceinline__ unsigned cvt_pk(float lo, float hi) { unsigned r; asm("v_cvt_pk_bf16_f32 %0, %1, %2" : "=v"(r) : "v"(lo), "v"(hi)); return r; }
;     __device__ __forceinline__ void operator()(AccRef acc, const pg8::Unit& u, int wr, int wc, int, int) const {
;     ...
;                 v4u pw[4][2];
; #pragma unroll
;                 for (int m = 0; m < 4; ++m) { const int row = u.pm * 256 + ai * 128 + wr * 64 + m * 16 + fr;
; #pragma unroll
;                     for (int bj = 0; bj < 2; ++bj) pw[m][bj] = *(const v4u*)(RB + (size_t)row * DM + u.pn * 256 + bj * 128 + wc * 32 + 8 * fq); }
; #pragma unroll
;                 for (int m = 0; m < 4; ++m)
; #pragma unroll
;                     for (int bj = 0; bj < 2; ++bj) { const v4u w = pw[m][bj]; r0[m][bj] = (f32x4){bf_lo(w.x), bf_hi(w.x), bf_lo(w.y), bf_hi(w.y)}; r1[m][bj] = (f32x4){bf_lo(w.z), bf_hi(w.z), bf_lo(w.w), bf_hi(w.w)}; }
;             }
;             asm volatile("" ::: "memory");
; #pragma unroll
;             for (int m = 0; m < 4; ++m) {
;                 const int row = u.pm * 256 + ai * 128 + wr * 64 + m * 16 + fr;
;                 float ss = 0.f;
; #pragma unroll
;                 for (int bj = 0; bj < 2; ++bj) {
;                     const int c0 = u.pn * 256 + bj * 128 + wc * 32 + 8 * fq;
;                     const f32x4 o0 = r0[m][bj] + acc[ai][bj][m][0], o1 = r1[m][bj] + acc[ai][bj][m][1];
;                     v4u w; w.x = cvt_pk(o0[0], o0[1]); w.y = cvt_pk(o0[2], o0[3]); w.z = cvt_pk(o1[0], o1[1]); w.w = cvt_pk(o1[2], o1[3]);
;                     *(v4u*)(HB + (size_t)row * DM + c0) = w;
.Lp5a_epi:
	s_mov_b64 s[30:31], s[44:45]
	s_mov_b64 s[42:43], s[46:47]
	s_add_u32 s30, s30, 0x7800000
	v_mov_b32_e32 v141, v196
	s_addc_u32 s31, s31, 0
	s_lshl_b32 s42, s68, 8
	s_add_i32 s42, s42, s35
	v_and_or_b32 v140, v141, 15, s42
	s_lshl_b32 s42, s67, 8
	v_ashrrev_i32_e32 v141, 1, v141
	v_and_b32_e32 v142, -8, v141
	s_or_b32 s43, s42, s28
	v_add_u32_e32 v186, s43, v142
	s_ashr_i32 s43, s42, 31
	s_lshl_b64 s[42:43], s[42:43], 1
	s_add_u32 s42, s30, s42
	s_addc_u32 s43, s31, s43
	s_add_u32 s42, s42, s48
	s_addc_u32 s43, s43, 0
	v_ashrrev_i32_e32 v143, 31, v142
	v_ashrrev_i32_e32 v141, 31, v140
	v_lshl_add_u64 v[142:143], v[142:143], 1, s[42:43]
	v_lshlrev_b64 v[188:189], 11, v[140:141]
	v_lshl_add_u64 v[144:145], v[142:143], 0, v[188:189]
	global_load_dwordx4 v[146:149], v[144:145], off nt
	global_load_dwordx4 v[158:161], v[144:145], off offset:256 nt
	v_or_b32_e32 v144, 16, v140
	v_ashrrev_i32_e32 v145, 31, v144
	v_lshlrev_b64 v[190:191], 11, v[144:145]
	v_lshl_add_u64 v[144:145], v[142:143], 0, v[190:191]
	global_load_dwordx4 v[162:165], v[144:145], off nt
	global_load_dwordx4 v[166:169], v[144:145], off offset:256 nt
	v_or_b32_e32 v144, 32, v140
	v_ashrrev_i32_e32 v145, 31, v144
	v_lshlrev_b64 v[192:193], 11, v[144:145]
	v_lshl_add_u64 v[144:145], v[142:143], 0, v[192:193]
	global_load_dwordx4 v[170:173], v[144:145], off nt
	global_load_dwordx4 v[174:177], v[144:145], off offset:256 nt
	v_or_b32_e32 v144, 48, v140
	v_ashrrev_i32_e32 v145, 31, v144
	v_lshlrev_b64 v[144:145], 11, v[144:145]
	v_lshl_add_u64 v[150:151], v[142:143], 0, v[144:145]
	global_load_dwordx4 v[178:181], v[150:151], off nt
	global_load_dwordx4 v[182:185], v[150:151], off offset:256 nt
	v_ashrrev_i32_e32 v187, 31, v186
	s_and_b64 vcc, exec, s[6:7]
	s_waitcnt vmcnt(0)
	v_lshlrev_b32_e32 v194, 16, v146
	v_and_b32_e32 v195, 0xffff0000, v146
	v_lshlrev_b32_e32 v202, 16, v148
	v_and_b32_e32 v203, 0xffff0000, v148
	v_lshlrev_b32_e32 v200, 16, v147
	v_and_b32_e32 v201, 0xffff0000, v147
	v_lshlrev_b32_e32 v204, 16, v149
	v_and_b32_e32 v205, 0xffff0000, v149
	v_pk_add_f32 v[124:125], v[124:125], v[194:195]
	v_pk_add_f32 v[120:121], v[120:121], v[202:203]
	v_pk_add_f32 v[126:127], v[126:127], v[200:201]
	v_lshlrev_b32_e32 v206, 16, v158
	v_and_b32_e32 v207, 0xffff0000, v158
	v_lshlrev_b32_e32 v158, 16, v159
	v_and_b32_e32 v159, 0xffff0000, v159
	v_lshlrev_b32_e32 v208, 16, v160
	v_lshlrev_b32_e32 v146, 16, v184
	v_and_b32_e32 v147, 0xffff0000, v184
	v_lshlrev_b32_e32 v150, 16, v185
	v_and_b32_e32 v151, 0xffff0000, v185
	v_lshl_add_u64 v[184:185], s[30:31], 0, v[188:189]
	v_pk_add_f32 v[188:189], v[122:123], v[204:205]
	v_cvt_pk_bf16_f32 v122, v124, v125
	v_cvt_pk_bf16_f32 v124, v120, v121
	v_lshlrev_b64 v[120:121], 1, v[186:187]
	v_and_b32_e32 v209, 0xffff0000, v160
	v_lshlrev_b32_e32 v160, 16, v161
	v_and_b32_e32 v161, 0xffff0000, v161
	v_cvt_pk_bf16_f32 v123, v126, v127
	v_lshl_add_u64 v[126:127], v[184:185], 0, v[120:121]
	v_cvt_pk_bf16_f32 v125, v188, v189
	global_store_dwordx4 v[126:127], v[122:125], off
	v_pk_add_f32 v[118:119], v[118:119], v[158:159]
	v_pk_add_f32 v[116:117], v[116:117], v[206:207]
	v_pk_add_f32 v[122:123], v[110:111], v[160:161]
	v_pk_add_f32 v[110:111], v[108:109], v[208:209]
	v_cvt_pk_bf16_f32 v108, v116, v117
	v_cvt_pk_bf16_f32 v109, v118, v119
	v_lshlrev_b32_e32 v210, 16, v162
	v_and_b32_e32 v211, 0xffff0000, v162
	v_lshlrev_b32_e32 v162, 16, v163
	v_and_b32_e32 v163, 0xffff0000, v163
	v_lshlrev_b32_e32 v212, 16, v164
	v_and_b32_e32 v213, 0xffff0000, v164
	v_lshlrev_b32_e32 v164, 16, v165
	v_and_b32_e32 v165, 0xffff0000, v165
	v_cvt_pk_bf16_f32 v110, v110, v111
	v_cvt_pk_bf16_f32 v111, v122, v123
	global_store_dwordx4 v[126:127], v[108:111], off offset:256
	v_lshlrev_b32_e32 v214, 16, v166
	v_and_b32_e32 v215, 0xffff0000, v166
	v_lshl_add_u64 v[108:109], s[30:31], 0, v[190:191]
	v_lshlrev_b32_e32 v166, 16, v167
	v_and_b32_e32 v167, 0xffff0000, v167
	v_lshlrev_b32_e32 v216, 16, v168
	v_and_b32_e32 v217, 0xffff0000, v168
	v_lshlrev_b32_e32 v168, 16, v169
	v_and_b32_e32 v169, 0xffff0000, v169
	v_pk_add_f32 v[110:111], v[114:115], v[162:163]
	v_pk_add_f32 v[112:113], v[112:113], v[210:211]
	v_pk_add_f32 v[114:115], v[106:107], v[164:165]
	v_pk_add_f32 v[106:107], v[104:105], v[212:213]
	v_cvt_pk_bf16_f32 v104, v112, v113
	v_cvt_pk_bf16_f32 v105, v110, v111
	v_lshl_add_u64 v[108:109], v[108:109], 0, v[120:121]
	v_cvt_pk_bf16_f32 v106, v106, v107
	v_cvt_pk_bf16_f32 v107, v114, v115
	global_store_dwordx4 v[108:109], v[104:107], off
	v_pk_add_f32 v[102:103], v[102:103], v[166:167]
	v_pk_add_f32 v[100:101], v[100:101], v[214:215]
	v_pk_add_f32 v[104:105], v[94:95], v[168:169]
	v_pk_add_f32 v[94:95], v[92:93], v[216:217]
	v_cvt_pk_bf16_f32 v92, v100, v101
	v_cvt_pk_bf16_f32 v93, v102, v103
	v_lshlrev_b32_e32 v218, 16, v170
	v_and_b32_e32 v219, 0xffff0000, v170
	v_lshlrev_b32_e32 v170, 16, v171
	v_and_b32_e32 v171, 0xffff0000, v171
	v_lshlrev_b32_e32 v220, 16, v172
	v_and_b32_e32 v221, 0xffff0000, v172
	v_lshlrev_b32_e32 v172, 16, v173
	v_and_b32_e32 v173, 0xffff0000, v173
	v_cvt_pk_bf16_f32 v94, v94, v95
	v_cvt_pk_bf16_f32 v95, v104, v105
	global_store_dwordx4 v[108:109], v[92:95], off offset:256
	v_lshlrev_b32_e32 v222, 16, v174
	v_and_b32_e32 v223, 0xffff0000, v174
	v_lshl_add_u64 v[92:93], s[30:31], 0, v[192:193]
	v_lshlrev_b32_e32 v174, 16, v175
	v_and_b32_e32 v175, 0xffff0000, v175
	v_lshlrev_b32_e32 v224, 16, v176
	v_and_b32_e32 v225, 0xffff0000, v176
	v_lshlrev_b32_e32 v176, 16, v177
	v_and_b32_e32 v177, 0xffff0000, v177
	v_pk_add_f32 v[94:95], v[98:99], v[170:171]
	v_pk_add_f32 v[96:97], v[96:97], v[218:219]
	v_pk_add_f32 v[98:99], v[90:91], v[172:173]
; __device__ __forceinline__ unsigned cvt_pk(float lo, float hi) { unsigned r; asm("v_cvt_pk_bf16_f32 %0, %1, %2" : "=v"(r) : "v"(lo), "v"(hi)); return r; }
;     __device__ __forceinline__ void operator()(AccRef acc, const pg8::Unit& u, int wr, int wc, int, int) const {
;     ...
;                 for (int m = 0; m < 4; ++m) { const int row = u.pm * 256 + ai * 128 + wr * 64 + m * 16 + fr;
; #pragma unroll
;                     for (int bj = 0; bj < 2; ++bj) pw[m][bj] = *(const v4u*)(RB + (size_t)row * DM + u.pn * 256 + bj * 128 + wc * 32 + 8 * fq); }
; #pragma unroll
;                 for (int m = 0; m < 4; ++m)
; #pragma unroll
;                     for (int bj = 0; bj < 2; ++bj) { const v4u w = pw[m][bj]; r0[m][bj] = (f32x4){bf_lo(w.x), bf_hi(w.x), bf_lo(w.y), bf_hi(w.y)}; r1[m][bj] = (f32x4){bf_lo(w.z), bf_hi(w.z), bf_lo(w.w), bf_hi(w.w)}; }
;             }
;             asm volatile("" ::: "memory");
; #pragma unroll
;             for (int m = 0; m < 4; ++m) {
;                 const int row = u.pm * 256 + ai * 128 + wr * 64 + m * 16 + fr;
;                 float ss = 0.f;
; #pragma unroll
;                 for (int bj = 0; bj < 2; ++bj) {
;                     const int c0 = u.pn * 256 + bj * 128 + wc * 32 + 8 * fq;
;                     const f32x4 o0 = r0[m][bj] + acc[ai][bj][m][0], o1 = r1[m][bj] + acc[ai][bj][m][1];
;                     v4u w; w.x = cvt_pk(o0[0], o0[1]); w.y = cvt_pk(o0[2], o0[3]); w.z = cvt_pk(o1[0], o1[1]); w.w = cvt_pk(o1[2], o1[3]);
;                     *(v4u*)(HB + (size_t)row * DM + c0) = w;
	v_pk_add_f32 v[90:91], v[88:89], v[220:221]
	v_cvt_pk_bf16_f32 v88, v96, v97
	v_cvt_pk_bf16_f32 v89, v94, v95
	v_lshl_add_u64 v[92:93], v[92:93], 0, v[120:121]
	v_cvt_pk_bf16_f32 v90, v90, v91
	v_cvt_pk_bf16_f32 v91, v98, v99
	global_store_dwordx4 v[92:93], v[88:91], off
	v_pk_add_f32 v[86:87], v[86:87], v[174:175]
	v_pk_add_f32 v[84:85], v[84:85], v[222:223]
	v_pk_add_f32 v[88:89], v[78:79], v[176:177]
	v_pk_add_f32 v[78:79], v[76:77], v[224:225]
	v_cvt_pk_bf16_f32 v76, v84, v85
	v_cvt_pk_bf16_f32 v77, v86, v87
	v_lshlrev_b32_e32 v226, 16, v178
	v_and_b32_e32 v227, 0xffff0000, v178
	v_lshlrev_b32_e32 v178, 16, v179
	v_and_b32_e32 v179, 0xffff0000, v179
	v_lshlrev_b32_e32 v228, 16, v180
	v_and_b32_e32 v229, 0xffff0000, v180
	v_lshlrev_b32_e32 v180, 16, v181
	v_and_b32_e32 v181, 0xffff0000, v181
	v_cvt_pk_bf16_f32 v78, v78, v79
	v_cvt_pk_bf16_f32 v79, v88, v89
	global_store_dwordx4 v[92:93], v[76:79], off offset:256
	v_lshlrev_b32_e32 v148, 16, v182
	v_and_b32_e32 v149, 0xffff0000, v182
	v_lshl_add_u64 v[76:77], s[30:31], 0, v[144:145]
	v_pk_add_f32 v[78:79], v[82:83], v[178:179]
	v_pk_add_f32 v[80:81], v[80:81], v[226:227]
	v_pk_add_f32 v[82:83], v[74:75], v[180:181]
	v_pk_add_f32 v[74:75], v[72:73], v[228:229]
	v_cvt_pk_bf16_f32 v72, v80, v81
	v_cvt_pk_bf16_f32 v73, v78, v79
	v_lshl_add_u64 v[76:77], v[76:77], 0, v[120:121]
	v_lshlrev_b32_e32 v182, 16, v183
	v_and_b32_e32 v183, 0xffff0000, v183
	v_cvt_pk_bf16_f32 v74, v74, v75
	v_cvt_pk_bf16_f32 v75, v82, v83
	global_store_dwordx4 v[76:77], v[72:75], off
	v_pk_add_f32 v[68:69], v[68:69], v[148:149]
	v_pk_add_f32 v[70:71], v[70:71], v[182:183]
	v_pk_add_f32 v[72:73], v[66:67], v[150:151]
	v_pk_add_f32 v[66:67], v[64:65], v[146:147]
	v_cvt_pk_bf16_f32 v64, v68, v69
	v_cvt_pk_bf16_f32 v65, v70, v71
	s_nop 0
	v_cvt_pk_bf16_f32 v66, v66, v67
	v_cvt_pk_bf16_f32 v67, v72, v73
	global_store_dwordx4 v[76:77], v[64:67], off offset:256
	s_nop 1
	v_add_u32_e32 v64, 0x80, v140
	v_ashrrev_i32_e32 v65, 31, v64
	v_lshlrev_b64 v[98:99], 11, v[64:65]
	v_lshl_add_u64 v[64:65], v[142:143], 0, v[98:99]
	global_load_dwordx4 v[66:69], v[64:65], off nt
	global_load_dwordx4 v[70:73], v[64:65], off offset:256 nt
	v_add_u32_e32 v64, 0x90, v140
	v_ashrrev_i32_e32 v65, 31, v64
	v_lshlrev_b64 v[100:101], 11, v[64:65]
	v_lshl_add_u64 v[64:65], v[142:143], 0, v[100:101]
	global_load_dwordx4 v[74:77], v[64:65], off nt
	global_load_dwordx4 v[78:81], v[64:65], off offset:256 nt
	v_add_u32_e32 v64, 0xa0, v140
	v_ashrrev_i32_e32 v65, 31, v64
	v_lshlrev_b64 v[102:103], 11, v[64:65]
	v_lshl_add_u64 v[64:65], v[142:143], 0, v[102:103]
	global_load_dwordx4 v[82:85], v[64:65], off nt
	global_load_dwordx4 v[86:89], v[64:65], off offset:256 nt
	v_add_u32_e32 v64, 0xb0, v140
	v_ashrrev_i32_e32 v65, 31, v64
	v_lshlrev_b64 v[64:65], 11, v[64:65]
	v_lshl_add_u64 v[94:95], v[142:143], 0, v[64:65]
	global_load_dwordx4 v[90:93], v[94:95], off nt
	s_nop 0
	global_load_dwordx4 v[94:97], v[94:95], off offset:256 nt
	v_lshl_add_u64 v[98:99], s[30:31], 0, v[98:99]
	s_waitcnt vmcnt(7)
	v_lshlrev_b32_e32 v104, 16, v66
	v_and_b32_e32 v105, 0xffff0000, v66
	v_lshlrev_b32_e32 v106, 16, v67
	v_and_b32_e32 v107, 0xffff0000, v67
	v_lshlrev_b32_e32 v108, 16, v68
	v_and_b32_e32 v109, 0xffff0000, v68
	v_lshlrev_b32_e32 v110, 16, v69
	v_and_b32_e32 v111, 0xffff0000, v69
	v_pk_add_f32 v[60:61], v[60:61], v[104:105]
	s_waitcnt vmcnt(6)
	v_lshlrev_b32_e32 v112, 16, v70
	v_and_b32_e32 v113, 0xffff0000, v70
	v_lshlrev_b32_e32 v70, 16, v71
	v_and_b32_e32 v71, 0xffff0000, v71
	v_lshlrev_b32_e32 v114, 16, v72
	v_and_b32_e32 v115, 0xffff0000, v72
	v_lshlrev_b32_e32 v72, 16, v73
	v_and_b32_e32 v73, 0xffff0000, v73
	v_pk_add_f32 v[62:63], v[62:63], v[106:107]
	v_pk_add_f32 v[104:105], v[58:59], v[110:111]
	v_pk_add_f32 v[58:59], v[56:57], v[108:109]
	v_cvt_pk_bf16_f32 v56, v60, v61
	v_cvt_pk_bf16_f32 v57, v62, v63
	v_lshl_add_u64 v[60:61], v[98:99], 0, v[120:121]
	v_cvt_pk_bf16_f32 v58, v58, v59
	v_cvt_pk_bf16_f32 v59, v104, v105
	global_store_dwordx4 v[60:61], v[56:59], off
	v_pk_add_f32 v[54:55], v[54:55], v[70:71]
	v_pk_add_f32 v[52:53], v[52:53], v[112:113]
	v_pk_add_f32 v[56:57], v[46:47], v[72:73]
	v_pk_add_f32 v[46:47], v[44:45], v[114:115]
	v_cvt_pk_bf16_f32 v44, v52, v53
	v_cvt_pk_bf16_f32 v45, v54, v55
	s_waitcnt vmcnt(6)
; __device__ __forceinline__ unsigned cvt_pk(float lo, float hi) { unsigned r; asm("v_cvt_pk_bf16_f32 %0, %1, %2" : "=v"(r) : "v"(lo), "v"(hi)); return r; }
; #define PG8_BAR __builtin_amdgcn_s_barrier()
; template <int KK, class Epi, class Sched, bool ALIGN_EPI = true>
; __device__ __forceinline__ void gemm_phase(LAS unsigned char* lds, const bf16* gA, const bf16* gBt, const Sched& S, const Epi& E, const int wid) {
;     ...
;         if constexpr (ALIGN_EPI) { if (wr == 0) PG8_BAR; }
;         E(acc, cur, wr, wc, fr, fq);
;         if (!has_next) break;
; #pragma unroll
;         for (int a = 0; a < 2; ++a)
; #pragma unroll
;             for (int b = 0; b < 2; ++b)
; #pragma unroll
;                 for (int m = 0; m < 4; ++m)
; #pragma unroll
;                     for (int n = 0; n < 2; ++n) acc[a][b][m][n] = (f32x4){0.f, 0.f, 0.f, 0.f};
;         cur = nxt; cA = nA; cB = nB; ++ui;
;         if constexpr (ALIGN_EPI) { if (wr == 1) PG8_BAR; }
;     __device__ __forceinline__ void operator()(AccRef acc, const pg8::Unit& u, int wr, int wc, int, int) const {
;     ...
;             for (int m = 0; m < 4; ++m) {
;                 const int row = u.pm * 256 + ai * 128 + wr * 64 + m * 16 + fr;
;                 float ss = 0.f;
; #pragma unroll
;                 for (int bj = 0; bj < 2; ++bj) {
;                     const int c0 = u.pn * 256 + bj * 128 + wc * 32 + 8 * fq;
;                     const f32x4 o0 = r0[m][bj] + acc[ai][bj][m][0], o1 = r1[m][bj] + acc[ai][bj][m][1];
;                     v4u w; w.x = cvt_pk(o0[0], o0[1]); w.y = cvt_pk(o0[2], o0[3]); w.z = cvt_pk(o1[0], o1[1]); w.w = cvt_pk(o1[2], o1[3]);
;                     *(v4u*)(HB + (size_t)row * DM + c0) = w;
	v_lshlrev_b32_e32 v116, 16, v74
	v_and_b32_e32 v117, 0xffff0000, v74
	v_lshlrev_b32_e32 v74, 16, v75
	v_and_b32_e32 v75, 0xffff0000, v75
	v_lshlrev_b32_e32 v118, 16, v76
	v_and_b32_e32 v119, 0xffff0000, v76
	v_lshlrev_b32_e32 v76, 16, v77
	v_and_b32_e32 v77, 0xffff0000, v77
	v_cvt_pk_bf16_f32 v46, v46, v47
	v_cvt_pk_bf16_f32 v47, v56, v57
	global_store_dwordx4 v[60:61], v[44:47], off offset:256
	s_waitcnt vmcnt(6)
	v_lshlrev_b32_e32 v122, 16, v78
	v_and_b32_e32 v123, 0xffff0000, v78
	v_lshl_add_u64 v[44:45], s[30:31], 0, v[100:101]
	v_lshlrev_b32_e32 v78, 16, v79
	v_and_b32_e32 v79, 0xffff0000, v79
	v_lshlrev_b32_e32 v124, 16, v80
	v_and_b32_e32 v125, 0xffff0000, v80
	v_lshlrev_b32_e32 v80, 16, v81
	v_and_b32_e32 v81, 0xffff0000, v81
	v_pk_add_f32 v[46:47], v[50:51], v[74:75]
	v_pk_add_f32 v[48:49], v[48:49], v[116:117]
	v_pk_add_f32 v[50:51], v[42:43], v[76:77]
	v_pk_add_f32 v[42:43], v[40:41], v[118:119]
	v_cvt_pk_bf16_f32 v40, v48, v49
	v_cvt_pk_bf16_f32 v41, v46, v47
	v_lshl_add_u64 v[44:45], v[44:45], 0, v[120:121]
	v_cvt_pk_bf16_f32 v42, v42, v43
	v_cvt_pk_bf16_f32 v43, v50, v51
	global_store_dwordx4 v[44:45], v[40:43], off
	v_pk_add_f32 v[38:39], v[38:39], v[78:79]
	v_pk_add_f32 v[36:37], v[36:37], v[122:123]
	v_pk_add_f32 v[40:41], v[30:31], v[80:81]
	v_pk_add_f32 v[30:31], v[28:29], v[124:125]
	v_cvt_pk_bf16_f32 v28, v36, v37
	v_cvt_pk_bf16_f32 v29, v38, v39
	s_waitcnt vmcnt(6)
	v_lshlrev_b32_e32 v126, 16, v82
	v_and_b32_e32 v127, 0xffff0000, v82
	v_lshlrev_b32_e32 v82, 16, v83
	v_and_b32_e32 v83, 0xffff0000, v83
	v_lshlrev_b32_e32 v140, 16, v84
	v_and_b32_e32 v141, 0xffff0000, v84
	v_lshlrev_b32_e32 v84, 16, v85
	v_and_b32_e32 v85, 0xffff0000, v85
	v_cvt_pk_bf16_f32 v30, v30, v31
	v_cvt_pk_bf16_f32 v31, v40, v41
	global_store_dwordx4 v[44:45], v[28:31], off offset:256
	s_waitcnt vmcnt(6)
	v_lshlrev_b32_e32 v142, 16, v86
	v_and_b32_e32 v143, 0xffff0000, v86
	v_lshl_add_u64 v[28:29], s[30:31], 0, v[102:103]
	v_lshlrev_b32_e32 v86, 16, v87
	v_and_b32_e32 v87, 0xffff0000, v87
	v_lshlrev_b32_e32 v144, 16, v88
	v_and_b32_e32 v145, 0xffff0000, v88
	v_lshlrev_b32_e32 v88, 16, v89
	v_and_b32_e32 v89, 0xffff0000, v89
	v_pk_add_f32 v[30:31], v[34:35], v[82:83]
	v_pk_add_f32 v[32:33], v[32:33], v[126:127]
	v_pk_add_f32 v[34:35], v[26:27], v[84:85]
	v_pk_add_f32 v[26:27], v[24:25], v[140:141]
	v_cvt_pk_bf16_f32 v24, v32, v33
	v_cvt_pk_bf16_f32 v25, v30, v31
	v_lshl_add_u64 v[28:29], v[28:29], 0, v[120:121]
	v_cvt_pk_bf16_f32 v26, v26, v27
	v_cvt_pk_bf16_f32 v27, v34, v35
	global_store_dwordx4 v[28:29], v[24:27], off
	v_pk_add_f32 v[22:23], v[22:23], v[86:87]
	v_pk_add_f32 v[20:21], v[20:21], v[142:143]
	v_pk_add_f32 v[24:25], v[14:15], v[88:89]
	v_pk_add_f32 v[14:15], v[12:13], v[144:145]
	v_cvt_pk_bf16_f32 v12, v20, v21
	v_cvt_pk_bf16_f32 v13, v22, v23
	s_waitcnt vmcnt(6)
	v_lshlrev_b32_e32 v146, 16, v90
	v_and_b32_e32 v147, 0xffff0000, v90
	v_lshlrev_b32_e32 v90, 16, v91
	v_and_b32_e32 v91, 0xffff0000, v91
	v_lshlrev_b32_e32 v148, 16, v92
	v_and_b32_e32 v149, 0xffff0000, v92
	v_lshlrev_b32_e32 v92, 16, v93
	v_and_b32_e32 v93, 0xffff0000, v93
	v_cvt_pk_bf16_f32 v14, v14, v15
	v_cvt_pk_bf16_f32 v15, v24, v25
	global_store_dwordx4 v[28:29], v[12:15], off offset:256
	s_waitcnt vmcnt(6)
	v_lshlrev_b32_e32 v66, 16, v96
	v_and_b32_e32 v67, 0xffff0000, v96
	v_lshl_add_u64 v[12:13], s[30:31], 0, v[64:65]
	v_lshlrev_b32_e32 v96, 16, v97
	v_and_b32_e32 v97, 0xffff0000, v97
	v_pk_add_f32 v[14:15], v[18:19], v[90:91]
	v_pk_add_f32 v[16:17], v[16:17], v[146:147]
	v_pk_add_f32 v[18:19], v[10:11], v[92:93]
	v_pk_add_f32 v[10:11], v[8:9], v[148:149]
	v_cvt_pk_bf16_f32 v8, v16, v17
	v_cvt_pk_bf16_f32 v9, v14, v15
	v_lshl_add_u64 v[12:13], v[12:13], 0, v[120:121]
	v_lshlrev_b32_e32 v68, 16, v94
	v_and_b32_e32 v69, 0xffff0000, v94
	v_lshlrev_b32_e32 v94, 16, v95
	v_and_b32_e32 v95, 0xffff0000, v95
	v_cvt_pk_bf16_f32 v10, v10, v11
	v_cvt_pk_bf16_f32 v11, v18, v19
	global_store_dwordx4 v[12:13], v[8:11], off
	s_mov_b64 s[30:31], -1
	v_pk_add_f32 v[6:7], v[6:7], v[94:95]
	v_pk_add_f32 v[8:9], v[2:3], v[96:97]
	v_pk_add_f32 v[2:3], v[0:1], v[66:67]
	v_pk_add_f32 v[4:5], v[4:5], v[68:69]
	v_cvt_pk_bf16_f32 v1, v6, v7
	v_cvt_pk_bf16_f32 v2, v2, v3
	v_cvt_pk_bf16_f32 v3, v8, v9
	s_nop 0
	v_cvt_pk_bf16_f32 v0, v4, v5
	global_store_dwordx4 v[12:13], v[0:3], off offset:256
	s_cbranch_vccnz .LBB0_660
	s_andn2_b64 vcc, exec, s[12:13]
	s_cbranch_vccnz .LBB0_659
	s_barrier
	s_branch .LBB0_659

; __device__ __forceinline__ float fexp2(float x) { return __builtin_amdgcn_exp2f(x); }
; __device__ __forceinline__ float frcp(float x) { return __builtin_amdgcn_rcpf(x); }
;     __device__ __forceinline__ void operator()(AccRef acc, const pg8::Unit& u, int wr, int wc, int, int) const {
;     ...
;             for (int m = 0; m < 4; ++m) { const int row = u.pm * 256 + ai * 128 + wr * 64 + m * 16 + fr;
; #pragma unroll
;                 for (int bj = 0; bj < 2; ++bj) { const size_t off = (size_t)row * DM + u.pn * 256 + bj * 128 + wc * 32 + 8 * fq; hwv[m][bj] = *(const v4u*)(HB + off); pwv[m][bj] = *(const v4u*)(XB + off); } }
;             asm volatile("" ::: "memory");
; #pragma unroll
;             for (int m = 0; m < 4; ++m) {
;                 const int row = u.pm * 256 + ai * 128 + wr * 64 + m * 16 + fr;
;                 float ss = 0.f;
; #pragma unroll
;                 for (int bj = 0; bj < 2; ++bj) {
;                     const int c0 = u.pn * 256 + bj * 128 + wc * 32 + 8 * fq;
;                     const v4u hw = hwv[m][bj], pw = pwv[m][bj];
;                     const float hh[8] = {bf_lo(hw.x), bf_hi(hw.x), bf_lo(hw.y), bf_hi(hw.y), bf_lo(hw.z), bf_hi(hw.z), bf_lo(hw.w), bf_hi(hw.w)};
;                     const float pp[8] = {bf_lo(pw.x), bf_hi(pw.x), bf_lo(pw.y), bf_hi(pw.y), bf_lo(pw.z), bf_hi(pw.z), bf_lo(pw.w), bf_hi(pw.w)};
;                     float o[8];
; #pragma unroll
;                     for (int j = 0; j < 4; ++j) {
;                         o[j] = hh[j] + pp[j] * frcp(1.0f + fexp2(-acc[ai][bj][m][0][j] * LOG2E));
;                         o[4 + j] = hh[4 + j] + pp[4 + j] * frcp(1.0f + fexp2(-acc[ai][bj][m][1][j] * LOG2E));
;                     }
.LBB0_833:
	s_mov_b64 s[42:43], s[44:45]
	s_mov_b64 s[48:49], s[46:47]
	s_add_u32 s54, s42, 0x7800000
	s_addc_u32 s55, s43, 0
	s_add_u32 s48, s42, 0x3600000
	s_addc_u32 s49, s43, 0
	s_add_u32 s42, s42, 0x43000
	v_mov_b32_e32 v134, v196
	s_addc_u32 s43, s43, 0
	s_lshl_b32 s15, s52, 8
	s_add_i32 s15, s15, s35
	s_lshl_b32 s50, s50, 8
	v_ashrrev_i32_e32 v128, 1, v134
	v_and_or_b32 v190, v134, 15, s15
	s_ashr_i32 s51, s50, 31
	v_and_b32_e32 v128, -8, v128
	v_ashrrev_i32_e32 v129, 31, v128
	s_or_b64 s[62:63], s[50:51], s[28:29]
	v_ashrrev_i32_e32 v191, 31, v190
	v_lshl_add_u64 v[188:189], s[62:63], 0, v[128:129]
	v_lshlrev_b64 v[130:131], 10, v[190:191]
	v_lshl_add_u64 v[130:131], v[188:189], 0, v[130:131]
	v_lshlrev_b64 v[130:131], 1, v[130:131]
	v_lshl_add_u64 v[132:133], s[54:55], 0, v[130:131]
	v_lshl_add_u64 v[130:131], s[48:49], 0, v[130:131]
	global_load_dwordx4 v[204:207], v[132:133], off nt
	global_load_dwordx4 v[212:215], v[132:133], off offset:256 nt
	global_load_dwordx4 v[208:211], v[130:131], off nt
	global_load_dwordx4 v[216:219], v[130:131], off offset:256 nt
	v_mul_f32_e32 v124, 0xbfb8aa3b, v124
	v_exp_f32_e32 v124, v124
	v_mul_f32_e32 v120, 0xbfb8aa3b, v120
	v_exp_f32_e32 v120, v120
	v_mul_f32_e32 v125, 0xbfb8aa3b, v125
	v_add_f32_e32 v124, 1.0, v124
	v_rcp_f32_e32 v225, v124
	v_or_b32_e32 v194, 16, v190
	v_or_b32_e32 v192, 32, v190
	v_or_b32_e32 v124, 48, v190
	v_exp_f32_e32 v224, v125
	v_add_f32_e32 v120, 1.0, v120
	s_or_b32 s15, s50, s28
	v_ashrrev_i32_e32 v195, 31, v194
	v_ashrrev_i32_e32 v193, 31, v192
	v_ashrrev_i32_e32 v125, 31, v124
	v_cmp_gt_u32_e32 vcc, 16, v134
	v_rcp_f32_e32 v226, v120
	v_add_u32_e32 v120, s15, v128
	v_lshlrev_b64 v[128:129], 11, v[190:191]
	v_lshlrev_b64 v[134:135], 10, v[194:195]
	v_lshlrev_b64 v[136:137], 10, v[192:193]
	v_lshlrev_b64 v[138:139], 10, v[124:125]
	v_lshl_add_u64 v[220:221], s[48:49], 0, v[128:129]
	v_lshl_add_u64 v[128:129], v[134:135], 0, v[188:189]
	v_lshl_add_u64 v[134:135], v[136:137], 0, v[188:189]
	v_lshl_add_u64 v[136:137], v[138:139], 0, v[188:189]
	v_lshlrev_b64 v[128:129], 1, v[128:129]
	v_lshlrev_b64 v[134:135], 1, v[134:135]
	v_lshlrev_b64 v[132:133], 1, v[136:137]
	v_lshl_add_u64 v[130:131], s[54:55], 0, v[128:129]
	v_lshl_add_u64 v[128:129], s[48:49], 0, v[128:129]
	v_lshl_add_u64 v[136:137], s[54:55], 0, v[134:135]
	v_lshl_add_u64 v[134:135], s[48:49], 0, v[134:135]
	v_lshl_add_u64 v[138:139], s[54:55], 0, v[132:133]
	v_lshl_add_u64 v[222:223], s[48:49], 0, v[132:133]
	global_load_dwordx4 v[172:175], v[130:131], off nt
	global_load_dwordx4 v[164:167], v[130:131], off offset:256 nt
	global_load_dwordx4 v[168:171], v[128:129], off nt
	global_load_dwordx4 v[160:163], v[128:129], off offset:256 nt
	global_load_dwordx4 v[156:159], v[136:137], off nt
	global_load_dwordx4 v[148:151], v[136:137], off offset:256 nt
	global_load_dwordx4 v[152:155], v[134:135], off nt
	global_load_dwordx4 v[144:147], v[134:135], off offset:256 nt
	global_load_dwordx4 v[140:143], v[138:139], off nt
	s_nop 0
	global_load_dwordx4 v[132:135], v[138:139], off offset:256 nt
	s_nop 0
	global_load_dwordx4 v[136:139], v[222:223], off nt
	global_load_dwordx4 v[128:131], v[222:223], off offset:256 nt
	v_mul_f32_e32 v121, 0xbfb8aa3b, v121
	v_exp_f32_e32 v121, v121
	v_mul_f32_e32 v126, 0xbfb8aa3b, v126
	v_exp_f32_e32 v126, v126
	v_mul_f32_e32 v112, 0xbfb8aa3b, v112
	v_add_f32_e32 v121, 1.0, v121
	v_rcp_f32_e32 v121, v121
	v_exp_f32_e32 v112, v112
	v_mul_f32_e32 v122, 0xbfb8aa3b, v122
	v_mul_f32_e32 v123, 0xbfb8aa3b, v123
	v_exp_f32_e32 v122, v122
	v_exp_f32_e32 v123, v123
	v_add_f32_e32 v112, 1.0, v112
	v_mul_f32_e32 v113, 0xbfb8aa3b, v113
	v_rcp_f32_e32 v112, v112
	v_exp_f32_e32 v113, v113
	v_add_f32_e32 v224, 1.0, v224
	v_add_f32_e32 v122, 1.0, v122
	v_add_f32_e32 v123, 1.0, v123
	v_rcp_f32_e32 v224, v224
	v_rcp_f32_e32 v122, v122
	v_rcp_f32_e32 v123, v123
	v_mul_f32_e32 v114, 0xbfb8aa3b, v114
	v_exp_f32_e32 v114, v114
	v_mul_f32_e32 v116, 0xbfb8aa3b, v116
	v_exp_f32_e32 v116, v116
	v_mul_f32_e32 v117, 0xbfb8aa3b, v117
	v_exp_f32_e32 v117, v117
	v_mul_f32_e32 v115, 0xbfb8aa3b, v115
	v_add_f32_e32 v116, 1.0, v116
	v_rcp_f32_e32 v116, v116
	v_add_f32_e32 v117, 1.0, v117
	v_rcp_f32_e32 v117, v117
	v_exp_f32_e32 v115, v115
	s_waitcnt vmcnt(0)
; __device__ __forceinline__ unsigned cvt_pk(float lo, float hi) { unsigned r; asm("v_cvt_pk_bf16_f32 %0, %1, %2" : "=v"(r) : "v"(lo), "v"(hi)); return r; }
; __device__ __forceinline__ float fexp2(float x) { return __builtin_amdgcn_exp2f(x); }
; __device__ __forceinline__ float frcp(float x) { return __builtin_amdgcn_rcpf(x); }
;     __device__ __forceinline__ void operator()(AccRef acc, const pg8::Unit& u, int wr, int wc, int, int) const {
;     ...
;                     const v4u hw = hwv[m][bj], pw = pwv[m][bj];
;                     const float hh[8] = {bf_lo(hw.x), bf_hi(hw.x), bf_lo(hw.y), bf_hi(hw.y), bf_lo(hw.z), bf_hi(hw.z), bf_lo(hw.w), bf_hi(hw.w)};
;                     const float pp[8] = {bf_lo(pw.x), bf_hi(pw.x), bf_lo(pw.y), bf_hi(pw.y), bf_lo(pw.z), bf_hi(pw.z), bf_lo(pw.w), bf_hi(pw.w)};
;                     float o[8];
; #pragma unroll
;                     for (int j = 0; j < 4; ++j) {
;                         o[j] = hh[j] + pp[j] * frcp(1.0f + fexp2(-acc[ai][bj][m][0][j] * LOG2E));
;                         o[4 + j] = hh[4 + j] + pp[4 + j] * frcp(1.0f + fexp2(-acc[ai][bj][m][1][j] * LOG2E));
;                     }
;                     v4u w; w.x = cvt_pk(o[0], o[1]); w.y = cvt_pk(o[2], o[3]); w.z = cvt_pk(o[4], o[5]); w.w = cvt_pk(o[6], o[7]);
;                     *(v4u*)(XB + (size_t)row * DM + c0) = w;
; #pragma unroll
;                     for (int j = 0; j < 8; ++j) ss += o[j] * o[j];
;                 }
;                 ss += __shfl_xor(ss, 16); ss += __shfl_xor(ss, 32);
;                 if (fq == 0) __hip_atomic_fetch_add(ssq + row, ss, __ATOMIC_RELAXED, __HIP_MEMORY_SCOPE_AGENT);
	v_lshlrev_b32_e32 v229, 16, v206
	v_and_b32_e32 v230, 0xffff0000, v206
	v_lshlrev_b32_e32 v231, 16, v207
	v_and_b32_e32 v232, 0xffff0000, v207
	v_lshlrev_b32_e32 v206, 16, v209
	v_and_b32_e32 v207, 0xffff0000, v209
	v_and_b32_e32 v209, 0xffff0000, v210
	v_fmac_f32_e32 v230, v121, v209
	v_add_f32_e32 v121, 1.0, v126
	v_mul_f32_e32 v126, 0xbfb8aa3b, v127
	v_rcp_f32_e32 v121, v121
	v_exp_f32_e32 v126, v126
	v_lshlrev_b32_e32 v222, 16, v204
	v_and_b32_e32 v223, 0xffff0000, v204
	v_lshlrev_b32_e32 v227, 16, v205
	v_and_b32_e32 v228, 0xffff0000, v205
	v_lshlrev_b32_e32 v204, 16, v208
	v_and_b32_e32 v205, 0xffff0000, v208
	v_lshlrev_b32_e32 v208, 16, v210
	v_fmac_f32_e32 v229, v226, v208
	v_add_f32_e32 v126, 1.0, v126
	v_fmac_f32_e32 v227, v121, v206
	v_lshlrev_b32_e32 v127, 16, v213
	v_and_b32_e32 v208, 0xffff0000, v213
	v_lshlrev_b32_e32 v209, 16, v214
	v_lshlrev_b32_e32 v121, 16, v216
	v_and_b32_e32 v213, 0xffff0000, v216
	v_lshlrev_b32_e32 v216, 16, v218
	v_rcp_f32_e32 v126, v126
	v_fmac_f32_e32 v209, v112, v216
	v_add_f32_e32 v112, 1.0, v113
	v_mul_f32_e32 v113, 0xbfb8aa3b, v118
	v_rcp_f32_e32 v112, v112
	v_exp_f32_e32 v113, v113
	v_lshlrev_b32_e32 v210, 16, v211
	v_and_b32_e32 v211, 0xffff0000, v211
	v_fmac_f32_e32 v223, v224, v205
	v_fmac_f32_e32 v231, v122, v210
	v_fmac_f32_e32 v228, v126, v207
	v_fmac_f32_e32 v232, v123, v211
	v_lshlrev_b32_e32 v123, 16, v212
	v_and_b32_e32 v126, 0xffff0000, v212
	v_and_b32_e32 v210, 0xffff0000, v214
	v_lshlrev_b32_e32 v211, 16, v215
	v_and_b32_e32 v212, 0xffff0000, v215
	v_lshlrev_b32_e32 v214, 16, v217
	v_and_b32_e32 v215, 0xffff0000, v217
	v_and_b32_e32 v217, 0xffff0000, v218
	v_fmac_f32_e32 v222, v225, v204
	v_mul_f32_e32 v122, v223, v223
	v_fmac_f32_e32 v210, v112, v217
	v_add_f32_e32 v112, 1.0, v113
	v_add_f32_e32 v113, 1.0, v114
	v_mul_f32_e32 v114, 0xbfb8aa3b, v119
	v_fmac_f32_e32 v122, v222, v222
	v_exp_f32_e32 v114, v114
	v_fmac_f32_e32 v122, v227, v227
	v_fmac_f32_e32 v122, v228, v228
	v_fmac_f32_e32 v122, v229, v229
	v_fmac_f32_e32 v122, v230, v230
	v_rcp_f32_e32 v112, v112
	v_add_f32_e32 v114, 1.0, v114
	v_fmac_f32_e32 v122, v231, v231
	v_rcp_f32_e32 v114, v114
	v_fmac_f32_e32 v122, v232, v232
	v_fmac_f32_e32 v123, v116, v121
	v_fmac_f32_e32 v126, v117, v213
	v_fmac_f32_e32 v122, v123, v123
	v_rcp_f32_e32 v113, v113
	v_add_f32_e32 v115, 1.0, v115
	v_fmac_f32_e32 v127, v112, v214
	v_fmac_f32_e32 v122, v126, v126
	v_rcp_f32_e32 v115, v115
	v_fmac_f32_e32 v208, v114, v215
	v_fmac_f32_e32 v122, v127, v127
	v_fmac_f32_e32 v122, v208, v208
	v_lshlrev_b32_e32 v218, 16, v219
	v_fmac_f32_e32 v122, v209, v209
	v_and_b32_e32 v219, 0xffff0000, v219
	v_fmac_f32_e32 v211, v113, v218
	v_fmac_f32_e32 v122, v210, v210
	v_fmac_f32_e32 v212, v115, v219
	v_fmac_f32_e32 v122, v211, v211
	v_fmac_f32_e32 v122, v212, v212
	ds_bpermute_b32 v112, v197, v122
	v_ashrrev_i32_e32 v121, 31, v120
	v_lshl_add_u64 v[118:119], v[120:121], 1, v[220:221]
	v_cvt_pk_bf16_f32 v204, v222, v223
	v_cvt_pk_bf16_f32 v205, v227, v228
	s_waitcnt lgkmcnt(0)
	v_add_f32_e32 v112, v122, v112
	ds_bpermute_b32 v113, v198, v112
	v_cvt_pk_bf16_f32 v206, v229, v230
	v_cvt_pk_bf16_f32 v207, v231, v232
	global_store_dwordx4 v[118:119], v[204:207], off
	v_cvt_pk_bf16_f32 v114, v123, v126
	v_cvt_pk_bf16_f32 v115, v127, v208
	v_cvt_pk_bf16_f32 v116, v209, v210
	v_cvt_pk_bf16_f32 v117, v211, v212
	global_store_dwordx4 v[118:119], v[114:117], off offset:256
	s_and_saveexec_b64 s[50:51], vcc
	s_cbranch_execz .LBB0_835
	s_waitcnt lgkmcnt(0)
	v_add_f32_e32 v114, v112, v113
	v_lshl_add_u64 v[112:113], v[190:191], 2, s[42:43]
	global_atomic_add_f32 v[112:113], v114, off

; __device__ __forceinline__ unsigned cvt_pk(float lo, float hi) { unsigned r; asm("v_cvt_pk_bf16_f32 %0, %1, %2" : "=v"(r) : "v"(lo), "v"(hi)); return r; }
; __device__ __forceinline__ float fexp2(float x) { return __builtin_amdgcn_exp2f(x); }
; __device__ __forceinline__ float frcp(float x) { return __builtin_amdgcn_rcpf(x); }
;     __device__ __forceinline__ void operator()(AccRef acc, const pg8::Unit& u, int wr, int wc, int, int) const {
;     ...
;             for (int m = 0; m < 4; ++m) { const int row = u.pm * 256 + ai * 128 + wr * 64 + m * 16 + fr;
; #pragma unroll
;                 for (int bj = 0; bj < 2; ++bj) { const size_t off = (size_t)row * DM + u.pn * 256 + bj * 128 + wc * 32 + 8 * fq; hwv[m][bj] = *(const v4u*)(HB + off); pwv[m][bj] = *(const v4u*)(XB + off); } }
;             asm volatile("" ::: "memory");
; #pragma unroll
;             for (int m = 0; m < 4; ++m) {
;                 const int row = u.pm * 256 + ai * 128 + wr * 64 + m * 16 + fr;
;                 float ss = 0.f;
; #pragma unroll
;                 for (int bj = 0; bj < 2; ++bj) {
;                     const int c0 = u.pn * 256 + bj * 128 + wc * 32 + 8 * fq;
;                     const v4u hw = hwv[m][bj], pw = pwv[m][bj];
;                     const float hh[8] = {bf_lo(hw.x), bf_hi(hw.x), bf_lo(hw.y), bf_hi(hw.y), bf_lo(hw.z), bf_hi(hw.z), bf_lo(hw.w), bf_hi(hw.w)};
;                     const float pp[8] = {bf_lo(pw.x), bf_hi(pw.x), bf_lo(pw.y), bf_hi(pw.y), bf_lo(pw.z), bf_hi(pw.z), bf_lo(pw.w), bf_hi(pw.w)};
;                     float o[8];
; #pragma unroll
;                     for (int j = 0; j < 4; ++j) {
;                         o[j] = hh[j] + pp[j] * frcp(1.0f + fexp2(-acc[ai][bj][m][0][j] * LOG2E));
;                         o[4 + j] = hh[4 + j] + pp[4 + j] * frcp(1.0f + fexp2(-acc[ai][bj][m][1][j] * LOG2E));
;                     }
;                     v4u w; w.x = cvt_pk(o[0], o[1]); w.y = cvt_pk(o[2], o[3]); w.z = cvt_pk(o[4], o[5]); w.w = cvt_pk(o[6], o[7]);
;                     *(v4u*)(XB + (size_t)row * DM + c0) = w;
; #pragma unroll
;                     for (int j = 0; j < 8; ++j) ss += o[j] * o[j];
;                 }
;                 ss += __shfl_xor(ss, 16); ss += __shfl_xor(ss, 32);
;                 if (fq == 0) __hip_atomic_fetch_add(ssq + row, ss, __ATOMIC_RELAXED, __HIP_MEMORY_SCOPE_AGENT);
.LBB0_841:
	s_or_b64 exec, exec, s[50:51]
	v_add_u32_e32 v118, 0x80, v190
	v_ashrrev_i32_e32 v119, 31, v118
	s_waitcnt lgkmcnt(0)
	v_lshlrev_b64 v[64:65], 10, v[118:119]
	v_lshl_add_u64 v[64:65], v[64:65], 0, v[188:189]
	v_lshlrev_b64 v[64:65], 1, v[64:65]
	v_lshl_add_u64 v[66:67], s[54:55], 0, v[64:65]
	v_lshl_add_u64 v[64:65], s[48:49], 0, v[64:65]
	global_load_dwordx4 v[122:125], v[66:67], off nt
	global_load_dwordx4 v[130:133], v[66:67], off offset:256 nt
	global_load_dwordx4 v[126:129], v[64:65], off nt
	global_load_dwordx4 v[134:137], v[64:65], off offset:256 nt
	v_add_u32_e32 v116, 0x90, v190
	v_add_u32_e32 v114, 0xa0, v190
	v_add_u32_e32 v112, 0xb0, v190
	v_mul_f32_e32 v60, 0xbfb8aa3b, v60
	v_mul_f32_e32 v56, 0xbfb8aa3b, v56
	v_mul_f32_e32 v61, 0xbfb8aa3b, v61
	v_mul_f32_e32 v57, 0xbfb8aa3b, v57
	v_ashrrev_i32_e32 v117, 31, v116
	v_ashrrev_i32_e32 v115, 31, v114
	v_ashrrev_i32_e32 v113, 31, v112
	v_exp_f32_e32 v72, v60
	v_exp_f32_e32 v73, v56
	v_exp_f32_e32 v74, v61
	v_exp_f32_e32 v75, v57
	v_lshlrev_b64 v[56:57], 10, v[116:117]
	v_lshlrev_b64 v[60:61], 10, v[114:115]
	v_lshlrev_b64 v[68:69], 10, v[112:113]
	v_lshl_add_u64 v[56:57], v[56:57], 0, v[188:189]
	v_lshl_add_u64 v[60:61], v[60:61], 0, v[188:189]
	v_lshl_add_u64 v[68:69], v[68:69], 0, v[188:189]
	v_lshlrev_b64 v[70:71], 11, v[118:119]
	v_lshlrev_b64 v[56:57], 1, v[56:57]
	v_lshlrev_b64 v[60:61], 1, v[60:61]
	v_lshlrev_b64 v[66:67], 1, v[68:69]
	v_lshl_add_u64 v[138:139], s[48:49], 0, v[70:71]
	v_lshl_add_u64 v[68:69], s[54:55], 0, v[56:57]
	v_lshl_add_u64 v[70:71], s[54:55], 0, v[60:61]
	v_lshl_add_u64 v[64:65], s[54:55], 0, v[66:67]
	v_lshl_add_u64 v[66:67], s[48:49], 0, v[66:67]
	v_lshl_add_u64 v[56:57], s[48:49], 0, v[56:57]
	v_lshl_add_u64 v[60:61], s[48:49], 0, v[60:61]
	v_add_f32_e32 v140, 1.0, v72
	v_add_f32_e32 v141, 1.0, v73
	v_add_f32_e32 v142, 1.0, v74
	v_add_f32_e32 v143, 1.0, v75
	global_load_dwordx4 v[108:111], v[68:69], off nt
	global_load_dwordx4 v[100:103], v[68:69], off offset:256 nt
	global_load_dwordx4 v[104:107], v[56:57], off nt
	global_load_dwordx4 v[96:99], v[56:57], off offset:256 nt
	global_load_dwordx4 v[92:95], v[70:71], off nt
	global_load_dwordx4 v[84:87], v[70:71], off offset:256 nt
	global_load_dwordx4 v[88:91], v[60:61], off nt
	global_load_dwordx4 v[80:83], v[60:61], off offset:256 nt
	global_load_dwordx4 v[76:79], v[64:65], off nt
	s_nop 0
	global_load_dwordx4 v[68:71], v[64:65], off offset:256 nt
	global_load_dwordx4 v[72:75], v[66:67], off nt
	s_nop 0
	global_load_dwordx4 v[64:67], v[66:67], off offset:256 nt
	v_mul_f32_e32 v58, 0xbfb8aa3b, v58
	v_exp_f32_e32 v58, v58
	v_rcp_f32_e32 v57, v141
	v_mul_f32_e32 v62, 0xbfb8aa3b, v62
	v_rcp_f32_e32 v60, v142
	v_exp_f32_e32 v62, v62
	v_rcp_f32_e32 v56, v140
	v_mul_f32_e32 v48, 0xbfb8aa3b, v48
	v_exp_f32_e32 v48, v48
	v_add_f32_e32 v62, 1.0, v62
	v_mul_f32_e32 v49, 0xbfb8aa3b, v49
	v_exp_f32_e32 v49, v49
	v_add_f32_e32 v48, 1.0, v48
	v_rcp_f32_e32 v48, v48
	v_rcp_f32_e32 v61, v143
	v_mul_f32_e32 v50, 0xbfb8aa3b, v50
	v_mul_f32_e32 v59, 0xbfb8aa3b, v59
	v_exp_f32_e32 v50, v50
	v_exp_f32_e32 v59, v59
	v_mul_f32_e32 v52, 0xbfb8aa3b, v52
	v_exp_f32_e32 v52, v52
	v_mul_f32_e32 v53, 0xbfb8aa3b, v53
	v_exp_f32_e32 v53, v53
	v_add_f32_e32 v59, 1.0, v59
	v_rcp_f32_e32 v59, v59
	v_add_f32_e32 v52, 1.0, v52
	v_rcp_f32_e32 v52, v52
	v_add_f32_e32 v53, 1.0, v53
	v_rcp_f32_e32 v53, v53
	v_mul_f32_e32 v51, 0xbfb8aa3b, v51
	v_exp_f32_e32 v51, v51
	s_waitcnt vmcnt(15)
	v_lshlrev_b32_e32 v142, 16, v124
	v_lshlrev_b32_e32 v140, 16, v122
	s_waitcnt vmcnt(13)
	v_lshlrev_b32_e32 v146, 16, v128
	v_fmac_f32_e32 v142, v57, v146
	v_add_f32_e32 v57, 1.0, v58
	v_mul_f32_e32 v58, 0xbfb8aa3b, v63
	v_exp_f32_e32 v58, v58
	v_lshlrev_b32_e32 v144, 16, v126
	v_fmac_f32_e32 v140, v56, v144
	v_rcp_f32_e32 v56, v62
	v_add_f32_e32 v58, 1.0, v58
	v_and_b32_e32 v122, 0xffff0000, v122
	v_and_b32_e32 v126, 0xffff0000, v126
	v_rcp_f32_e32 v58, v58
	v_fmac_f32_e32 v122, v60, v126
	v_rcp_f32_e32 v57, v57
	v_lshlrev_b32_e32 v141, 16, v123
	v_lshlrev_b32_e32 v145, 16, v127
	v_mul_f32_e32 v60, v122, v122
	v_and_b32_e32 v123, 0xffff0000, v123
	v_and_b32_e32 v127, 0xffff0000, v127
	v_fmac_f32_e32 v141, v56, v145
	v_fmac_f32_e32 v60, v140, v140
	v_lshlrev_b32_e32 v143, 16, v125
	v_lshlrev_b32_e32 v147, 16, v129
	v_fmac_f32_e32 v123, v58, v127
	v_fmac_f32_e32 v60, v141, v141
	v_fmac_f32_e32 v143, v57, v147
	v_cvt_pk_bf16_f32 v56, v140, v122
	v_cvt_pk_bf16_f32 v57, v141, v123
	v_fmac_f32_e32 v60, v123, v123
	v_lshlrev_b32_e32 v63, 16, v131
	v_and_b32_e32 v122, 0xffff0000, v131
	v_lshlrev_b32_e32 v123, 16, v132
	s_waitcnt vmcnt(12)
	v_lshlrev_b32_e32 v131, 16, v136
	v_fmac_f32_e32 v123, v48, v131
	v_add_f32_e32 v48, 1.0, v49
	v_mul_f32_e32 v49, 0xbfb8aa3b, v54
	v_rcp_f32_e32 v48, v48
	v_exp_f32_e32 v49, v49
	v_and_b32_e32 v124, 0xffff0000, v124
	v_and_b32_e32 v128, 0xffff0000, v128
	v_fmac_f32_e32 v124, v61, v128
	v_fmac_f32_e32 v60, v142, v142
	v_cvt_pk_bf16_f32 v58, v142, v124
	v_fmac_f32_e32 v60, v124, v124
	v_and_b32_e32 v124, 0xffff0000, v132
	v_and_b32_e32 v132, 0xffff0000, v136
	v_fmac_f32_e32 v124, v48, v132
	v_add_f32_e32 v48, 1.0, v49
	v_add_f32_e32 v49, 1.0, v50
	v_mul_f32_e32 v50, 0xbfb8aa3b, v55
	v_exp_f32_e32 v50, v50
	v_and_b32_e32 v125, 0xffff0000, v125
	v_and_b32_e32 v129, 0xffff0000, v129
	v_rcp_f32_e32 v48, v48
	v_add_f32_e32 v50, 1.0, v50
	v_fmac_f32_e32 v125, v59, v129
	v_fmac_f32_e32 v60, v143, v143
	v_lshlrev_b32_e32 v61, 16, v130
	v_lshlrev_b32_e32 v59, 16, v134
	v_rcp_f32_e32 v50, v50
	v_fmac_f32_e32 v60, v125, v125
	v_and_b32_e32 v62, 0xffff0000, v130
	v_and_b32_e32 v128, 0xffff0000, v134
	v_fmac_f32_e32 v61, v52, v59
	v_lshlrev_b32_e32 v129, 16, v135
	v_fmac_f32_e32 v62, v53, v128
	v_fmac_f32_e32 v60, v61, v61
	v_and_b32_e32 v130, 0xffff0000, v135
	v_rcp_f32_e32 v49, v49
	v_add_f32_e32 v51, 1.0, v51
	v_fmac_f32_e32 v63, v48, v129
	v_fmac_f32_e32 v60, v62, v62
	v_rcp_f32_e32 v51, v51
	v_fmac_f32_e32 v122, v50, v130
	v_fmac_f32_e32 v60, v63, v63
	v_fmac_f32_e32 v60, v122, v122
	v_lshlrev_b32_e32 v126, 16, v133
	v_and_b32_e32 v127, 0xffff0000, v133
	v_lshlrev_b32_e32 v133, 16, v137
	v_fmac_f32_e32 v60, v123, v123
	v_and_b32_e32 v134, 0xffff0000, v137
	v_fmac_f32_e32 v126, v49, v133
	v_fmac_f32_e32 v60, v124, v124
	v_fmac_f32_e32 v127, v51, v134
	v_fmac_f32_e32 v60, v126, v126
	v_fmac_f32_e32 v60, v127, v127
	ds_bpermute_b32 v48, v197, v60
	v_lshl_add_u64 v[54:55], v[120:121], 1, v[138:139]
	v_cvt_pk_bf16_f32 v59, v143, v125
	global_store_dwordx4 v[54:55], v[56:59], off
	v_cvt_pk_bf16_f32 v50, v61, v62
	s_waitcnt lgkmcnt(0)
	v_add_f32_e32 v48, v60, v48
	ds_bpermute_b32 v49, v198, v48
	v_cvt_pk_bf16_f32 v51, v63, v122
	v_cvt_pk_bf16_f32 v52, v123, v124
	v_cvt_pk_bf16_f32 v53, v126, v127
	global_store_dwordx4 v[54:55], v[50:53], off offset:256
	s_and_saveexec_b64 s[50:51], vcc
	s_cbranch_execz .LBB0_843
	s_waitcnt lgkmcnt(0)
	v_add_f32_e32 v50, v48, v49
	v_lshl_add_u64 v[48:49], v[118:119], 2, s[42:43]
	global_atomic_add_f32 v[48:49], v50, off

; __device__ __forceinline__ unsigned cvt_pk(float lo, float hi) { unsigned r; asm("v_cvt_pk_bf16_f32 %0, %1, %2" : "=v"(r) : "v"(lo), "v"(hi)); return r; }
;     __device__ __forceinline__ void operator()(AccRef acc, const pg8::Unit& u, int wr, int wc, int, int) const {
;     ...
;                 v4u pw[4][2];
; #pragma unroll
;                 for (int m = 0; m < 4; ++m) { const int row = u.pm * 256 + ai * 128 + wr * 64 + m * 16 + fr;
; #pragma unroll
;                     for (int bj = 0; bj < 2; ++bj) pw[m][bj] = *(const v4u*)(RB + (size_t)row * DM + u.pn * 256 + bj * 128 + wc * 32 + 8 * fq); }
; #pragma unroll
;                 for (int m = 0; m < 4; ++m)
; #pragma unroll
;                     for (int bj = 0; bj < 2; ++bj) { const v4u w = pw[m][bj]; r0[m][bj] = (f32x4){bf_lo(w.x), bf_hi(w.x), bf_lo(w.y), bf_hi(w.y)}; r1[m][bj] = (f32x4){bf_lo(w.z), bf_hi(w.z), bf_lo(w.w), bf_hi(w.w)}; }
;             }
;             asm volatile("" ::: "memory");
; #pragma unroll
;             for (int m = 0; m < 4; ++m) {
;                 const int row = u.pm * 256 + ai * 128 + wr * 64 + m * 16 + fr;
;                 float ss = 0.f;
; #pragma unroll
;                 for (int bj = 0; bj < 2; ++bj) {
;                     const int c0 = u.pn * 256 + bj * 128 + wc * 32 + 8 * fq;
;                     const f32x4 o0 = r0[m][bj] + acc[ai][bj][m][0], o1 = r1[m][bj] + acc[ai][bj][m][1];
;                     v4u w; w.x = cvt_pk(o0[0], o0[1]); w.y = cvt_pk(o0[2], o0[3]); w.z = cvt_pk(o1[0], o1[1]); w.w = cvt_pk(o1[2], o1[3]);
;                     *(v4u*)(HB + (size_t)row * DM + c0) = w;
;                     ss += (o0[0] * o0[0] + o0[1] * o0[1]) + (o0[2] * o0[2] + o0[3] * o0[3]) + (o1[0] * o1[0] + o1[1] * o1[1]) + (o1[2] * o1[2] + o1[3] * o1[3]);
;                 }
;                 if (ssq_off >= 0) { ss += __shfl_xor(ss, 16); ss += __shfl_xor(ss, 32); if (fq == 0) __hip_atomic_fetch_add(ssq + row, ss, __ATOMIC_RELAXED, __HIP_MEMORY_SCOPE_AGENT); }
.LBB0_1189:
	s_mov_b64 s[42:43], s[22:23]
	s_mov_b64 s[46:47], s[20:21]
	s_add_u32 s44, s46, 0x7800000
	s_addc_u32 s45, s47, 0
	s_add_u32 s42, s46, 0x64000
	s_addc_u32 s43, s47, 0
	s_lshl_b32 s15, s38, 8
	s_lshl_b32 s36, s36, 8
	v_mov_b32_e32 v187, v196
	s_add_i32 s15, s15, s35
	s_ashr_i32 s37, s36, 31
	s_nop 0
	v_and_or_b32 v166, v187, 15, s15
	s_or_b32 s15, s36, s28
	s_lshl_b64 s[36:37], s[36:37], 1
	s_add_u32 s17, s46, s36
	v_ashrrev_i32_e32 v128, 1, v187
	s_addc_u32 s37, s47, s37
	v_and_b32_e32 v164, -8, v128
	s_add_u32 s36, s17, s55
	s_addc_u32 s37, s37, 0
	v_ashrrev_i32_e32 v165, 31, v164
	v_lshl_add_u64 v[128:129], v[164:165], 1, s[36:37]
	v_ashrrev_i32_e32 v167, 31, v166
	v_lshl_add_u64 v[168:169], v[128:129], 0, s[12:13]
	v_lshlrev_b64 v[200:201], 11, v[166:167]
	v_lshl_add_u64 v[128:129], v[168:169], 0, v[200:201]
	global_load_dwordx4 v[188:191], v[128:129], off nt
	global_load_dwordx4 v[192:195], v[128:129], off offset:256 nt
	v_or_b32_e32 v176, 16, v166
	v_or_b32_e32 v174, 32, v166
	v_or_b32_e32 v170, 48, v166
	v_ashrrev_i32_e32 v177, 31, v176
	v_ashrrev_i32_e32 v175, 31, v174
	v_ashrrev_i32_e32 v171, 31, v170
	v_lshlrev_b64 v[180:181], 11, v[176:177]
	v_lshlrev_b64 v[178:179], 11, v[174:175]
	v_lshlrev_b64 v[172:173], 11, v[170:171]
	v_lshl_add_u64 v[128:129], v[168:169], 0, v[180:181]
	v_lshl_add_u64 v[130:131], v[168:169], 0, v[178:179]
	v_lshl_add_u64 v[202:203], v[168:169], 0, v[172:173]
	global_load_dwordx4 v[148:151], v[128:129], off nt
	global_load_dwordx4 v[144:147], v[128:129], off offset:256 nt
	global_load_dwordx4 v[140:143], v[130:131], off nt
	global_load_dwordx4 v[136:139], v[130:131], off offset:256 nt
	global_load_dwordx4 v[132:135], v[202:203], off nt
	s_nop 0
	global_load_dwordx4 v[128:131], v[202:203], off offset:256 nt
	v_cmp_gt_u32_e32 vcc, 16, v187
	v_add_u32_e32 v164, s15, v164
	v_ashrrev_i32_e32 v165, 31, v164
	v_lshl_add_u64 v[200:201], s[44:45], 0, v[200:201]
	s_waitcnt vmcnt(0)
	v_lshlrev_b32_e32 v202, 16, v188
	v_and_b32_e32 v203, 0xffff0000, v188
	v_lshlrev_b32_e32 v188, 16, v189
	v_and_b32_e32 v189, 0xffff0000, v189
	v_lshlrev_b32_e32 v206, 16, v192
	v_and_b32_e32 v207, 0xffff0000, v192
	v_lshlrev_b32_e32 v192, 16, v193
	v_and_b32_e32 v193, 0xffff0000, v193
	v_lshlrev_b32_e32 v204, 16, v190
	v_and_b32_e32 v205, 0xffff0000, v190
	v_lshlrev_b32_e32 v190, 16, v191
	v_and_b32_e32 v191, 0xffff0000, v191
	v_lshlrev_b32_e32 v208, 16, v194
	v_and_b32_e32 v209, 0xffff0000, v194
	v_pk_add_f32 v[126:127], v[126:127], v[188:189]
	v_pk_add_f32 v[124:125], v[124:125], v[202:203]
	v_pk_add_f32 v[118:119], v[118:119], v[192:193]
	v_pk_add_f32 v[116:117], v[116:117], v[206:207]
	v_lshlrev_b32_e32 v194, 16, v195
	v_and_b32_e32 v195, 0xffff0000, v195
	v_pk_add_f32 v[122:123], v[122:123], v[190:191]
	v_pk_add_f32 v[120:121], v[120:121], v[204:205]
	v_pk_add_f32 v[190:191], v[112:113], v[208:209]
	v_cvt_pk_bf16_f32 v112, v124, v125
	v_cvt_pk_bf16_f32 v113, v126, v127
	v_mul_f32_e32 v125, v125, v125
	v_mul_f32_e32 v127, v127, v127
	v_mul_f32_e32 v192, v117, v117
	v_mul_f32_e32 v193, v119, v119
	v_pk_add_f32 v[188:189], v[114:115], v[194:195]
	v_cvt_pk_bf16_f32 v114, v120, v121
	v_mul_f32_e32 v121, v121, v121
	v_mul_f32_e32 v194, v191, v191
	v_fmac_f32_e32 v125, v124, v124
	v_fmac_f32_e32 v127, v126, v126
	v_fmac_f32_e32 v192, v116, v116
	v_fmac_f32_e32 v193, v118, v118
	v_mul_f32_e32 v115, v123, v123
	v_mul_f32_e32 v187, v189, v189
	v_fmac_f32_e32 v121, v120, v120
	v_fmac_f32_e32 v194, v190, v190
	v_add_f32_e32 v120, v125, v127
	v_add_f32_e32 v124, v192, v193
	v_fmac_f32_e32 v115, v122, v122
	v_fmac_f32_e32 v187, v188, v188
	v_add_f32_e32 v120, v121, v120
	v_add_f32_e32 v121, v194, v124
	v_add_f32_e32 v115, v115, v120
	v_add_f32_e32 v120, v187, v121
	v_add_f32_e32 v124, v115, v120
	ds_bpermute_b32 v125, v197, v124
	v_lshl_add_u64 v[120:121], v[164:165], 1, v[200:201]
	v_cvt_pk_bf16_f32 v115, v122, v123
	global_store_dwordx4 v[120:121], v[112:115], off
	s_waitcnt lgkmcnt(0)
	s_nop 0
	v_add_f32_e32 v112, v124, v125
	ds_bpermute_b32 v113, v198, v112
	v_cvt_pk_bf16_f32 v114, v116, v117
	v_cvt_pk_bf16_f32 v115, v118, v119
	v_cvt_pk_bf16_f32 v116, v190, v191
	v_cvt_pk_bf16_f32 v117, v188, v189
	global_store_dwordx4 v[120:121], v[114:117], off offset:256
	s_and_saveexec_b64 s[36:37], vcc
	s_cbranch_execz .LBB0_1191
	s_waitcnt lgkmcnt(0)
	v_add_f32_e32 v114, v112, v113
	v_lshl_add_u64 v[112:113], v[166:167], 2, s[42:43]
	global_atomic_add_f32 v[112:113], v114, off

; __device__ __forceinline__ unsigned cvt_pk(float lo, float hi) { unsigned r; asm("v_cvt_pk_bf16_f32 %0, %1, %2" : "=v"(r) : "v"(lo), "v"(hi)); return r; }
;     __device__ __forceinline__ void operator()(AccRef acc, const pg8::Unit& u, int wr, int wc, int, int) const {
;     ...
;                 for (int m = 0; m < 4; ++m) { const int row = u.pm * 256 + ai * 128 + wr * 64 + m * 16 + fr;
; #pragma unroll
;                     for (int bj = 0; bj < 2; ++bj) pw[m][bj] = *(const v4u*)(RB + (size_t)row * DM + u.pn * 256 + bj * 128 + wc * 32 + 8 * fq); }
; #pragma unroll
;                 for (int m = 0; m < 4; ++m)
; #pragma unroll
;                     for (int bj = 0; bj < 2; ++bj) { const v4u w = pw[m][bj]; r0[m][bj] = (f32x4){bf_lo(w.x), bf_hi(w.x), bf_lo(w.y), bf_hi(w.y)}; r1[m][bj] = (f32x4){bf_lo(w.z), bf_hi(w.z), bf_lo(w.w), bf_hi(w.w)}; }
;             }
;             asm volatile("" ::: "memory");
; #pragma unroll
;             for (int m = 0; m < 4; ++m) {
;                 const int row = u.pm * 256 + ai * 128 + wr * 64 + m * 16 + fr;
;                 float ss = 0.f;
; #pragma unroll
;                 for (int bj = 0; bj < 2; ++bj) {
;                     const int c0 = u.pn * 256 + bj * 128 + wc * 32 + 8 * fq;
;                     const f32x4 o0 = r0[m][bj] + acc[ai][bj][m][0], o1 = r1[m][bj] + acc[ai][bj][m][1];
;                     v4u w; w.x = cvt_pk(o0[0], o0[1]); w.y = cvt_pk(o0[2], o0[3]); w.z = cvt_pk(o1[0], o1[1]); w.w = cvt_pk(o1[2], o1[3]);
;                     *(v4u*)(HB + (size_t)row * DM + c0) = w;
;                     ss += (o0[0] * o0[0] + o0[1] * o0[1]) + (o0[2] * o0[2] + o0[3] * o0[3]) + (o1[0] * o1[0] + o1[1] * o1[1]) + (o1[2] * o1[2] + o1[3] * o1[3]);
;                 }
;                 if (ssq_off >= 0) { ss += __shfl_xor(ss, 16); ss += __shfl_xor(ss, 32); if (fq == 0) __hip_atomic_fetch_add(ssq + row, ss, __ATOMIC_RELAXED, __HIP_MEMORY_SCOPE_AGENT); }
.LBB0_1197:
	s_or_b64 exec, exec, s[36:37]
	v_add_u32_e32 v98, 0x80, v166
	v_ashrrev_i32_e32 v99, 31, v98
	v_lshlrev_b64 v[110:111], 11, v[98:99]
	s_waitcnt lgkmcnt(0)
	v_lshl_add_u64 v[64:65], v[168:169], 0, v[110:111]
	global_load_dwordx4 v[102:105], v[64:65], off nt
	global_load_dwordx4 v[106:109], v[64:65], off offset:256 nt
	v_add_u32_e32 v94, 0x90, v166
	v_add_u32_e32 v92, 0xa0, v166
	v_add_u32_e32 v88, 0xb0, v166
	v_ashrrev_i32_e32 v95, 31, v94
	v_ashrrev_i32_e32 v93, 31, v92
	v_ashrrev_i32_e32 v89, 31, v88
	v_lshlrev_b64 v[100:101], 11, v[94:95]
	v_lshlrev_b64 v[96:97], 11, v[92:93]
	v_lshlrev_b64 v[90:91], 11, v[88:89]
	v_lshl_add_u64 v[64:65], v[168:169], 0, v[100:101]
	v_lshl_add_u64 v[66:67], v[168:169], 0, v[96:97]
	v_lshl_add_u64 v[112:113], v[168:169], 0, v[90:91]
	global_load_dwordx4 v[84:87], v[64:65], off nt
	global_load_dwordx4 v[80:83], v[64:65], off offset:256 nt
	global_load_dwordx4 v[76:79], v[66:67], off nt
	global_load_dwordx4 v[72:75], v[66:67], off offset:256 nt
	global_load_dwordx4 v[68:71], v[112:113], off nt
	s_nop 0
	global_load_dwordx4 v[64:67], v[112:113], off offset:256 nt
	v_lshl_add_u64 v[110:111], s[44:45], 0, v[110:111]
	s_waitcnt vmcnt(7)
	v_lshlrev_b32_e32 v112, 16, v102
	v_and_b32_e32 v113, 0xffff0000, v102
	v_lshlrev_b32_e32 v102, 16, v103
	v_and_b32_e32 v103, 0xffff0000, v103
	s_waitcnt vmcnt(6)
	v_lshlrev_b32_e32 v116, 16, v106
	v_and_b32_e32 v117, 0xffff0000, v106
	v_lshlrev_b32_e32 v106, 16, v107
	v_and_b32_e32 v107, 0xffff0000, v107
	v_lshlrev_b32_e32 v114, 16, v104
	v_and_b32_e32 v115, 0xffff0000, v104
	v_lshlrev_b32_e32 v104, 16, v105
	v_and_b32_e32 v105, 0xffff0000, v105
	v_lshlrev_b32_e32 v118, 16, v108
	v_and_b32_e32 v119, 0xffff0000, v108
	v_lshlrev_b32_e32 v108, 16, v109
	v_and_b32_e32 v109, 0xffff0000, v109
	v_pk_add_f32 v[62:63], v[62:63], v[102:103]
	v_pk_add_f32 v[60:61], v[60:61], v[112:113]
	v_pk_add_f32 v[54:55], v[54:55], v[106:107]
	v_pk_add_f32 v[52:53], v[52:53], v[116:117]
	v_pk_add_f32 v[58:59], v[58:59], v[104:105]
	v_pk_add_f32 v[56:57], v[56:57], v[114:115]
	v_pk_add_f32 v[102:103], v[50:51], v[108:109]
	v_pk_add_f32 v[104:105], v[48:49], v[118:119]
	v_cvt_pk_bf16_f32 v48, v60, v61
	v_cvt_pk_bf16_f32 v49, v62, v63
	v_mul_f32_e32 v61, v61, v61
	v_mul_f32_e32 v63, v63, v63
	v_mul_f32_e32 v107, v53, v53
	v_mul_f32_e32 v108, v55, v55
	v_cvt_pk_bf16_f32 v50, v56, v57
	v_mul_f32_e32 v57, v57, v57
	v_mul_f32_e32 v109, v105, v105
	v_fmac_f32_e32 v61, v60, v60
	v_fmac_f32_e32 v63, v62, v62
	v_fmac_f32_e32 v107, v52, v52
	v_fmac_f32_e32 v108, v54, v54
	v_mul_f32_e32 v51, v59, v59
	v_mul_f32_e32 v106, v103, v103
	v_fmac_f32_e32 v57, v56, v56
	v_fmac_f32_e32 v109, v104, v104
	v_add_f32_e32 v56, v61, v63
	v_add_f32_e32 v60, v107, v108
	v_fmac_f32_e32 v51, v58, v58
	v_fmac_f32_e32 v106, v102, v102
	v_add_f32_e32 v56, v57, v56
	v_add_f32_e32 v57, v109, v60
	v_add_f32_e32 v51, v51, v56
	v_add_f32_e32 v56, v106, v57
	v_add_f32_e32 v60, v51, v56
	ds_bpermute_b32 v61, v197, v60
	v_lshl_add_u64 v[56:57], v[164:165], 1, v[110:111]
	v_cvt_pk_bf16_f32 v51, v58, v59
	global_store_dwordx4 v[56:57], v[48:51], off
	s_waitcnt lgkmcnt(0)
	s_nop 0
	v_add_f32_e32 v48, v60, v61
	ds_bpermute_b32 v49, v198, v48
	v_cvt_pk_bf16_f32 v50, v52, v53
	v_cvt_pk_bf16_f32 v51, v54, v55
	v_cvt_pk_bf16_f32 v52, v104, v105
	v_cvt_pk_bf16_f32 v53, v102, v103
	global_store_dwordx4 v[56:57], v[50:53], off offset:256
	s_and_saveexec_b64 s[36:37], vcc
	s_cbranch_execz .LBB0_1199
	s_waitcnt lgkmcnt(0)
	v_add_f32_e32 v50, v48, v49
	v_lshl_add_u64 v[48:49], v[98:99], 2, s[42:43]
	global_atomic_add_f32 v[48:49], v50, off

; __device__ __forceinline__ unsigned cvt_pk(float lo, float hi) { unsigned r; asm("v_cvt_pk_bf16_f32 %0, %1, %2" : "=v"(r) : "v"(lo), "v"(hi)); return r; }
;     __device__ __forceinline__ void operator()(AccRef acc, const pg8::Unit& u, int wr, int wc, int, int) const {
;     ...
;                 v4u pw[4][2];
; #pragma unroll
;                 for (int m = 0; m < 4; ++m) { const int row = u.pm * 256 + ai * 128 + wr * 64 + m * 16 + fr;
; #pragma unroll
;                     for (int bj = 0; bj < 2; ++bj) pw[m][bj] = *(const v4u*)(RB + (size_t)row * DM + u.pn * 256 + bj * 128 + wc * 32 + 8 * fq); }
; #pragma unroll
;                 for (int m = 0; m < 4; ++m)
; #pragma unroll
;                     for (int bj = 0; bj < 2; ++bj) { const v4u w = pw[m][bj]; r0[m][bj] = (f32x4){bf_lo(w.x), bf_hi(w.x), bf_lo(w.y), bf_hi(w.y)}; r1[m][bj] = (f32x4){bf_lo(w.z), bf_hi(w.z), bf_lo(w.w), bf_hi(w.w)}; }
;             }
;             asm volatile("" ::: "memory");
; #pragma unroll
;             for (int m = 0; m < 4; ++m) {
;                 const int row = u.pm * 256 + ai * 128 + wr * 64 + m * 16 + fr;
;                 float ss = 0.f;
; #pragma unroll
;                 for (int bj = 0; bj < 2; ++bj) {
;                     const int c0 = u.pn * 256 + bj * 128 + wc * 32 + 8 * fq;
;                     const f32x4 o0 = r0[m][bj] + acc[ai][bj][m][0], o1 = r1[m][bj] + acc[ai][bj][m][1];
;                     v4u w; w.x = cvt_pk(o0[0], o0[1]); w.y = cvt_pk(o0[2], o0[3]); w.z = cvt_pk(o1[0], o1[1]); w.w = cvt_pk(o1[2], o1[3]);
;                     *(v4u*)(HB + (size_t)row * DM + c0) = w;
.Lp5b_epi:
	s_mov_b64 s[24:25], s[20:21]
	s_mov_b64 s[26:27], s[22:23]
	s_add_u32 s24, s24, 0x7800000
	s_addc_u32 s25, s25, 0
	s_lshl_b32 s26, s58, 8
	v_mov_b32_e32 v141, v196
	s_add_i32 s26, s26, s35
	s_nop 0
	v_and_or_b32 v140, v141, 15, s26
	s_lshl_b32 s26, s57, 8
	s_ashr_i32 s27, s26, 31
	s_or_b32 s30, s26, s28
	s_lshl_b64 s[26:27], s[26:27], 1
	s_add_u32 s26, s24, s26
	v_ashrrev_i32_e32 v141, 1, v141
	s_addc_u32 s27, s25, s27
	v_and_b32_e32 v150, -8, v141
	s_add_u32 s26, s26, s43
	s_addc_u32 s27, s27, 0
	v_ashrrev_i32_e32 v151, 31, v150
	v_ashrrev_i32_e32 v141, 31, v140
	v_lshl_add_u64 v[142:143], v[150:151], 1, s[26:27]
	v_lshlrev_b64 v[186:187], 11, v[140:141]
	v_lshl_add_u64 v[144:145], v[142:143], 0, v[186:187]
	global_load_dwordx4 v[146:149], v[144:145], off nt
	global_load_dwordx4 v[158:161], v[144:145], off offset:256 nt
	v_or_b32_e32 v144, 16, v140
	v_ashrrev_i32_e32 v145, 31, v144
	v_lshlrev_b64 v[188:189], 11, v[144:145]
	v_lshl_add_u64 v[144:145], v[142:143], 0, v[188:189]
	global_load_dwordx4 v[162:165], v[144:145], off nt
	global_load_dwordx4 v[166:169], v[144:145], off offset:256 nt
	v_or_b32_e32 v144, 32, v140
	v_ashrrev_i32_e32 v145, 31, v144
	v_lshlrev_b64 v[190:191], 11, v[144:145]
	v_lshl_add_u64 v[144:145], v[142:143], 0, v[190:191]
	global_load_dwordx4 v[170:173], v[144:145], off nt
	global_load_dwordx4 v[174:177], v[144:145], off offset:256 nt
	v_or_b32_e32 v144, 48, v140
	v_ashrrev_i32_e32 v145, 31, v144
	v_lshlrev_b64 v[144:145], 11, v[144:145]
	v_lshl_add_u64 v[182:183], v[142:143], 0, v[144:145]
	global_load_dwordx4 v[178:181], v[182:183], off nt
	s_nop 0
	global_load_dwordx4 v[182:185], v[182:183], off offset:256 nt
	v_add_u32_e32 v192, s30, v150
	v_ashrrev_i32_e32 v193, 31, v192
	s_and_b64 vcc, exec, s[6:7]
	s_mov_b64 s[6:7], -1
	s_waitcnt vmcnt(0)
	v_lshlrev_b32_e32 v194, 16, v146
	v_and_b32_e32 v195, 0xffff0000, v146
	v_lshlrev_b32_e32 v202, 16, v148
	v_and_b32_e32 v203, 0xffff0000, v148
	v_lshlrev_b32_e32 v200, 16, v147
	v_and_b32_e32 v201, 0xffff0000, v147
	v_lshlrev_b32_e32 v204, 16, v149
	v_and_b32_e32 v205, 0xffff0000, v149
	v_pk_add_f32 v[124:125], v[124:125], v[194:195]
	v_pk_add_f32 v[120:121], v[120:121], v[202:203]
	v_pk_add_f32 v[126:127], v[126:127], v[200:201]
	v_lshlrev_b32_e32 v206, 16, v158
	v_and_b32_e32 v207, 0xffff0000, v158
	v_lshlrev_b32_e32 v158, 16, v159
	v_and_b32_e32 v159, 0xffff0000, v159
	v_lshlrev_b32_e32 v208, 16, v160
	v_lshlrev_b32_e32 v146, 16, v184
	v_and_b32_e32 v147, 0xffff0000, v184
	v_lshlrev_b32_e32 v150, 16, v185
	v_and_b32_e32 v151, 0xffff0000, v185
	v_lshl_add_u64 v[184:185], s[24:25], 0, v[186:187]
	v_pk_add_f32 v[186:187], v[122:123], v[204:205]
	v_cvt_pk_bf16_f32 v122, v124, v125
	v_cvt_pk_bf16_f32 v124, v120, v121
	v_lshlrev_b64 v[120:121], 1, v[192:193]
	v_and_b32_e32 v209, 0xffff0000, v160
	v_lshlrev_b32_e32 v160, 16, v161
	v_and_b32_e32 v161, 0xffff0000, v161
	v_cvt_pk_bf16_f32 v123, v126, v127
	v_lshl_add_u64 v[126:127], v[184:185], 0, v[120:121]
	v_cvt_pk_bf16_f32 v125, v186, v187
	global_store_dwordx4 v[126:127], v[122:125], off
	v_pk_add_f32 v[118:119], v[118:119], v[158:159]
	v_pk_add_f32 v[116:117], v[116:117], v[206:207]
	v_pk_add_f32 v[122:123], v[110:111], v[160:161]
	v_pk_add_f32 v[110:111], v[108:109], v[208:209]
	v_cvt_pk_bf16_f32 v108, v116, v117
	v_cvt_pk_bf16_f32 v109, v118, v119
	v_lshlrev_b32_e32 v210, 16, v162
	v_and_b32_e32 v211, 0xffff0000, v162
	v_lshlrev_b32_e32 v162, 16, v163
	v_and_b32_e32 v163, 0xffff0000, v163
	v_lshlrev_b32_e32 v212, 16, v164
	v_and_b32_e32 v213, 0xffff0000, v164
	v_lshlrev_b32_e32 v164, 16, v165
	v_and_b32_e32 v165, 0xffff0000, v165
	v_cvt_pk_bf16_f32 v110, v110, v111
	v_cvt_pk_bf16_f32 v111, v122, v123
	global_store_dwordx4 v[126:127], v[108:111], off offset:256
	v_lshlrev_b32_e32 v214, 16, v166
	v_and_b32_e32 v215, 0xffff0000, v166
	v_lshl_add_u64 v[108:109], s[24:25], 0, v[188:189]
	v_lshlrev_b32_e32 v166, 16, v167
	v_and_b32_e32 v167, 0xffff0000, v167
	v_lshlrev_b32_e32 v216, 16, v168
	v_and_b32_e32 v217, 0xffff0000, v168
	v_lshlrev_b32_e32 v168, 16, v169
	v_and_b32_e32 v169, 0xffff0000, v169
	v_pk_add_f32 v[110:111], v[114:115], v[162:163]
	v_pk_add_f32 v[112:113], v[112:113], v[210:211]
	v_pk_add_f32 v[114:115], v[106:107], v[164:165]
	v_pk_add_f32 v[106:107], v[104:105], v[212:213]
	v_cvt_pk_bf16_f32 v104, v112, v113
	v_cvt_pk_bf16_f32 v105, v110, v111
	v_lshl_add_u64 v[108:109], v[108:109], 0, v[120:121]
	v_cvt_pk_bf16_f32 v106, v106, v107
	v_cvt_pk_bf16_f32 v107, v114, v115
	global_store_dwordx4 v[108:109], v[104:107], off
	v_pk_add_f32 v[102:103], v[102:103], v[166:167]
	v_pk_add_f32 v[100:101], v[100:101], v[214:215]
	v_pk_add_f32 v[104:105], v[94:95], v[168:169]
	v_pk_add_f32 v[94:95], v[92:93], v[216:217]
	v_cvt_pk_bf16_f32 v92, v100, v101
	v_cvt_pk_bf16_f32 v93, v102, v103
	v_lshlrev_b32_e32 v218, 16, v170
	v_and_b32_e32 v219, 0xffff0000, v170
	v_lshlrev_b32_e32 v170, 16, v171
	v_and_b32_e32 v171, 0xffff0000, v171
	v_lshlrev_b32_e32 v220, 16, v172
	v_and_b32_e32 v221, 0xffff0000, v172
	v_lshlrev_b32_e32 v172, 16, v173
	v_and_b32_e32 v173, 0xffff0000, v173
	v_cvt_pk_bf16_f32 v94, v94, v95
	v_cvt_pk_bf16_f32 v95, v104, v105
	global_store_dwordx4 v[108:109], v[92:95], off offset:256
	v_lshlrev_b32_e32 v222, 16, v174
	v_and_b32_e32 v223, 0xffff0000, v174
	v_lshl_add_u64 v[92:93], s[24:25], 0, v[190:191]
	v_lshlrev_b32_e32 v174, 16, v175
	v_and_b32_e32 v175, 0xffff0000, v175
	v_lshlrev_b32_e32 v224, 16, v176
	v_and_b32_e32 v225, 0xffff0000, v176
	v_lshlrev_b32_e32 v176, 16, v177
	v_and_b32_e32 v177, 0xffff0000, v177
	v_pk_add_f32 v[94:95], v[98:99], v[170:171]
	v_pk_add_f32 v[96:97], v[96:97], v[218:219]
; __device__ __forceinline__ unsigned cvt_pk(float lo, float hi) { unsigned r; asm("v_cvt_pk_bf16_f32 %0, %1, %2" : "=v"(r) : "v"(lo), "v"(hi)); return r; }
;     __device__ __forceinline__ void operator()(AccRef acc, const pg8::Unit& u, int wr, int wc, int, int) const {
;     ...
;                 for (int m = 0; m < 4; ++m) { const int row = u.pm * 256 + ai * 128 + wr * 64 + m * 16 + fr;
; #pragma unroll
;                     for (int bj = 0; bj < 2; ++bj) pw[m][bj] = *(const v4u*)(RB + (size_t)row * DM + u.pn * 256 + bj * 128 + wc * 32 + 8 * fq); }
; #pragma unroll
;                 for (int m = 0; m < 4; ++m)
; #pragma unroll
;                     for (int bj = 0; bj < 2; ++bj) { const v4u w = pw[m][bj]; r0[m][bj] = (f32x4){bf_lo(w.x), bf_hi(w.x), bf_lo(w.y), bf_hi(w.y)}; r1[m][bj] = (f32x4){bf_lo(w.z), bf_hi(w.z), bf_lo(w.w), bf_hi(w.w)}; }
;             }
;             asm volatile("" ::: "memory");
; #pragma unroll
;             for (int m = 0; m < 4; ++m) {
;                 const int row = u.pm * 256 + ai * 128 + wr * 64 + m * 16 + fr;
;                 float ss = 0.f;
; #pragma unroll
;                 for (int bj = 0; bj < 2; ++bj) {
;                     const int c0 = u.pn * 256 + bj * 128 + wc * 32 + 8 * fq;
;                     const f32x4 o0 = r0[m][bj] + acc[ai][bj][m][0], o1 = r1[m][bj] + acc[ai][bj][m][1];
;                     v4u w; w.x = cvt_pk(o0[0], o0[1]); w.y = cvt_pk(o0[2], o0[3]); w.z = cvt_pk(o1[0], o1[1]); w.w = cvt_pk(o1[2], o1[3]);
;                     *(v4u*)(HB + (size_t)row * DM + c0) = w;
	v_pk_add_f32 v[98:99], v[90:91], v[172:173]
	v_pk_add_f32 v[90:91], v[88:89], v[220:221]
	v_cvt_pk_bf16_f32 v88, v96, v97
	v_cvt_pk_bf16_f32 v89, v94, v95
	v_lshl_add_u64 v[92:93], v[92:93], 0, v[120:121]
	v_cvt_pk_bf16_f32 v90, v90, v91
	v_cvt_pk_bf16_f32 v91, v98, v99
	global_store_dwordx4 v[92:93], v[88:91], off
	v_pk_add_f32 v[86:87], v[86:87], v[174:175]
	v_pk_add_f32 v[84:85], v[84:85], v[222:223]
	v_pk_add_f32 v[88:89], v[78:79], v[176:177]
	v_pk_add_f32 v[78:79], v[76:77], v[224:225]
	v_cvt_pk_bf16_f32 v76, v84, v85
	v_cvt_pk_bf16_f32 v77, v86, v87
	v_lshlrev_b32_e32 v226, 16, v178
	v_and_b32_e32 v227, 0xffff0000, v178
	v_lshlrev_b32_e32 v178, 16, v179
	v_and_b32_e32 v179, 0xffff0000, v179
	v_lshlrev_b32_e32 v228, 16, v180
	v_and_b32_e32 v229, 0xffff0000, v180
	v_lshlrev_b32_e32 v180, 16, v181
	v_and_b32_e32 v181, 0xffff0000, v181
	v_cvt_pk_bf16_f32 v78, v78, v79
	v_cvt_pk_bf16_f32 v79, v88, v89
	global_store_dwordx4 v[92:93], v[76:79], off offset:256
	v_lshlrev_b32_e32 v148, 16, v182
	v_and_b32_e32 v149, 0xffff0000, v182
	v_lshl_add_u64 v[76:77], s[24:25], 0, v[144:145]
	v_pk_add_f32 v[78:79], v[82:83], v[178:179]
	v_pk_add_f32 v[80:81], v[80:81], v[226:227]
	v_pk_add_f32 v[82:83], v[74:75], v[180:181]
	v_pk_add_f32 v[74:75], v[72:73], v[228:229]
	v_cvt_pk_bf16_f32 v72, v80, v81
	v_cvt_pk_bf16_f32 v73, v78, v79
	v_lshl_add_u64 v[76:77], v[76:77], 0, v[120:121]
	v_lshlrev_b32_e32 v182, 16, v183
	v_and_b32_e32 v183, 0xffff0000, v183
	v_cvt_pk_bf16_f32 v74, v74, v75
	v_cvt_pk_bf16_f32 v75, v82, v83
	global_store_dwordx4 v[76:77], v[72:75], off
	v_pk_add_f32 v[68:69], v[68:69], v[148:149]
	v_pk_add_f32 v[70:71], v[70:71], v[182:183]
	v_pk_add_f32 v[72:73], v[66:67], v[150:151]
	v_pk_add_f32 v[66:67], v[64:65], v[146:147]
	v_cvt_pk_bf16_f32 v64, v68, v69
	v_cvt_pk_bf16_f32 v65, v70, v71
	s_nop 0
	v_cvt_pk_bf16_f32 v66, v66, v67
	v_cvt_pk_bf16_f32 v67, v72, v73
	global_store_dwordx4 v[76:77], v[64:67], off offset:256
	s_nop 1
	v_add_u32_e32 v64, 0x80, v140
	v_ashrrev_i32_e32 v65, 31, v64
	v_lshlrev_b64 v[98:99], 11, v[64:65]
	v_lshl_add_u64 v[64:65], v[142:143], 0, v[98:99]
	global_load_dwordx4 v[66:69], v[64:65], off nt
	global_load_dwordx4 v[70:73], v[64:65], off offset:256 nt
	v_add_u32_e32 v64, 0x90, v140
	v_ashrrev_i32_e32 v65, 31, v64
	v_lshlrev_b64 v[100:101], 11, v[64:65]
	v_lshl_add_u64 v[64:65], v[142:143], 0, v[100:101]
	global_load_dwordx4 v[74:77], v[64:65], off nt
	global_load_dwordx4 v[78:81], v[64:65], off offset:256 nt
	v_add_u32_e32 v64, 0xa0, v140
	v_ashrrev_i32_e32 v65, 31, v64
	v_lshlrev_b64 v[102:103], 11, v[64:65]
	v_lshl_add_u64 v[64:65], v[142:143], 0, v[102:103]
	global_load_dwordx4 v[82:85], v[64:65], off nt
	global_load_dwordx4 v[86:89], v[64:65], off offset:256 nt
	v_add_u32_e32 v64, 0xb0, v140
	v_ashrrev_i32_e32 v65, 31, v64
	v_lshlrev_b64 v[64:65], 11, v[64:65]
	v_lshl_add_u64 v[94:95], v[142:143], 0, v[64:65]
	global_load_dwordx4 v[90:93], v[94:95], off nt
	s_nop 0
	global_load_dwordx4 v[94:97], v[94:95], off offset:256 nt
	v_lshl_add_u64 v[98:99], s[24:25], 0, v[98:99]
	s_waitcnt vmcnt(7)
	v_lshlrev_b32_e32 v104, 16, v66
	v_and_b32_e32 v105, 0xffff0000, v66
	v_lshlrev_b32_e32 v106, 16, v67
	v_and_b32_e32 v107, 0xffff0000, v67
	v_lshlrev_b32_e32 v108, 16, v68
	v_and_b32_e32 v109, 0xffff0000, v68
	v_lshlrev_b32_e32 v110, 16, v69
	v_and_b32_e32 v111, 0xffff0000, v69
	v_pk_add_f32 v[60:61], v[60:61], v[104:105]
	s_waitcnt vmcnt(6)
	v_lshlrev_b32_e32 v112, 16, v70
	v_and_b32_e32 v113, 0xffff0000, v70
	v_lshlrev_b32_e32 v70, 16, v71
	v_and_b32_e32 v71, 0xffff0000, v71
	v_lshlrev_b32_e32 v114, 16, v72
	v_and_b32_e32 v115, 0xffff0000, v72
	v_lshlrev_b32_e32 v72, 16, v73
	v_and_b32_e32 v73, 0xffff0000, v73
	v_pk_add_f32 v[62:63], v[62:63], v[106:107]
	v_pk_add_f32 v[104:105], v[58:59], v[110:111]
	v_pk_add_f32 v[58:59], v[56:57], v[108:109]
	v_cvt_pk_bf16_f32 v56, v60, v61
	v_cvt_pk_bf16_f32 v57, v62, v63
	v_lshl_add_u64 v[60:61], v[98:99], 0, v[120:121]
	v_cvt_pk_bf16_f32 v58, v58, v59
	v_cvt_pk_bf16_f32 v59, v104, v105
	global_store_dwordx4 v[60:61], v[56:59], off
	v_pk_add_f32 v[54:55], v[54:55], v[70:71]
	v_pk_add_f32 v[52:53], v[52:53], v[112:113]
	v_pk_add_f32 v[56:57], v[46:47], v[72:73]
	v_pk_add_f32 v[46:47], v[44:45], v[114:115]
	v_cvt_pk_bf16_f32 v44, v52, v53
	v_cvt_pk_bf16_f32 v45, v54, v55
	s_waitcnt vmcnt(6)
; __device__ __forceinline__ unsigned cvt_pk(float lo, float hi) { unsigned r; asm("v_cvt_pk_bf16_f32 %0, %1, %2" : "=v"(r) : "v"(lo), "v"(hi)); return r; }
; #define PG8_BAR __builtin_amdgcn_s_barrier()
; template <int KK, class Epi, class Sched, bool ALIGN_EPI = true>
; __device__ __forceinline__ void gemm_phase(LAS unsigned char* lds, const bf16* gA, const bf16* gBt, const Sched& S, const Epi& E, const int wid) {
;     ...
;         if constexpr (ALIGN_EPI) { if (wr == 0) PG8_BAR; }
;         E(acc, cur, wr, wc, fr, fq);
;         if (!has_next) break;
; #pragma unroll
;         for (int a = 0; a < 2; ++a)
; #pragma unroll
;             for (int b = 0; b < 2; ++b)
; #pragma unroll
;                 for (int m = 0; m < 4; ++m)
; #pragma unroll
;                     for (int n = 0; n < 2; ++n) acc[a][b][m][n] = (f32x4){0.f, 0.f, 0.f, 0.f};
;         cur = nxt; cA = nA; cB = nB; ++ui;
;         if constexpr (ALIGN_EPI) { if (wr == 1) PG8_BAR; }
;     __device__ __forceinline__ void operator()(AccRef acc, const pg8::Unit& u, int wr, int wc, int, int) const {
;     ...
;             for (int m = 0; m < 4; ++m) {
;                 const int row = u.pm * 256 + ai * 128 + wr * 64 + m * 16 + fr;
;                 float ss = 0.f;
; #pragma unroll
;                 for (int bj = 0; bj < 2; ++bj) {
;                     const int c0 = u.pn * 256 + bj * 128 + wc * 32 + 8 * fq;
;                     const f32x4 o0 = r0[m][bj] + acc[ai][bj][m][0], o1 = r1[m][bj] + acc[ai][bj][m][1];
;                     v4u w; w.x = cvt_pk(o0[0], o0[1]); w.y = cvt_pk(o0[2], o0[3]); w.z = cvt_pk(o1[0], o1[1]); w.w = cvt_pk(o1[2], o1[3]);
;                     *(v4u*)(HB + (size_t)row * DM + c0) = w;
	v_lshlrev_b32_e32 v116, 16, v74
	v_and_b32_e32 v117, 0xffff0000, v74
	v_lshlrev_b32_e32 v74, 16, v75
	v_and_b32_e32 v75, 0xffff0000, v75
	v_lshlrev_b32_e32 v118, 16, v76
	v_and_b32_e32 v119, 0xffff0000, v76
	v_lshlrev_b32_e32 v76, 16, v77
	v_and_b32_e32 v77, 0xffff0000, v77
	v_cvt_pk_bf16_f32 v46, v46, v47
	v_cvt_pk_bf16_f32 v47, v56, v57
	global_store_dwordx4 v[60:61], v[44:47], off offset:256
	s_waitcnt vmcnt(6)
	v_lshlrev_b32_e32 v122, 16, v78
	v_and_b32_e32 v123, 0xffff0000, v78
	v_lshl_add_u64 v[44:45], s[24:25], 0, v[100:101]
	v_lshlrev_b32_e32 v78, 16, v79
	v_and_b32_e32 v79, 0xffff0000, v79
	v_lshlrev_b32_e32 v124, 16, v80
	v_and_b32_e32 v125, 0xffff0000, v80
	v_lshlrev_b32_e32 v80, 16, v81
	v_and_b32_e32 v81, 0xffff0000, v81
	v_pk_add_f32 v[46:47], v[50:51], v[74:75]
	v_pk_add_f32 v[48:49], v[48:49], v[116:117]
	v_pk_add_f32 v[50:51], v[42:43], v[76:77]
	v_pk_add_f32 v[42:43], v[40:41], v[118:119]
	v_cvt_pk_bf16_f32 v40, v48, v49
	v_cvt_pk_bf16_f32 v41, v46, v47
	v_lshl_add_u64 v[44:45], v[44:45], 0, v[120:121]
	v_cvt_pk_bf16_f32 v42, v42, v43
	v_cvt_pk_bf16_f32 v43, v50, v51
	global_store_dwordx4 v[44:45], v[40:43], off
	v_pk_add_f32 v[38:39], v[38:39], v[78:79]
	v_pk_add_f32 v[36:37], v[36:37], v[122:123]
	v_pk_add_f32 v[40:41], v[30:31], v[80:81]
	v_pk_add_f32 v[30:31], v[28:29], v[124:125]
	v_cvt_pk_bf16_f32 v28, v36, v37
	v_cvt_pk_bf16_f32 v29, v38, v39
	s_waitcnt vmcnt(6)
	v_lshlrev_b32_e32 v126, 16, v82
	v_and_b32_e32 v127, 0xffff0000, v82
	v_lshlrev_b32_e32 v82, 16, v83
	v_and_b32_e32 v83, 0xffff0000, v83
	v_lshlrev_b32_e32 v140, 16, v84
	v_and_b32_e32 v141, 0xffff0000, v84
	v_lshlrev_b32_e32 v84, 16, v85
	v_and_b32_e32 v85, 0xffff0000, v85
	v_cvt_pk_bf16_f32 v30, v30, v31
	v_cvt_pk_bf16_f32 v31, v40, v41
	global_store_dwordx4 v[44:45], v[28:31], off offset:256
	s_waitcnt vmcnt(6)
	v_lshlrev_b32_e32 v142, 16, v86
	v_and_b32_e32 v143, 0xffff0000, v86
	v_lshl_add_u64 v[28:29], s[24:25], 0, v[102:103]
	v_lshlrev_b32_e32 v86, 16, v87
	v_and_b32_e32 v87, 0xffff0000, v87
	v_lshlrev_b32_e32 v144, 16, v88
	v_and_b32_e32 v145, 0xffff0000, v88
	v_lshlrev_b32_e32 v88, 16, v89
	v_and_b32_e32 v89, 0xffff0000, v89
	v_pk_add_f32 v[30:31], v[34:35], v[82:83]
	v_pk_add_f32 v[32:33], v[32:33], v[126:127]
	v_pk_add_f32 v[34:35], v[26:27], v[84:85]
	v_pk_add_f32 v[26:27], v[24:25], v[140:141]
	v_cvt_pk_bf16_f32 v24, v32, v33
	v_cvt_pk_bf16_f32 v25, v30, v31
	v_lshl_add_u64 v[28:29], v[28:29], 0, v[120:121]
	v_cvt_pk_bf16_f32 v26, v26, v27
	v_cvt_pk_bf16_f32 v27, v34, v35
	global_store_dwordx4 v[28:29], v[24:27], off
	v_pk_add_f32 v[22:23], v[22:23], v[86:87]
	v_pk_add_f32 v[20:21], v[20:21], v[142:143]
	v_pk_add_f32 v[24:25], v[14:15], v[88:89]
	v_pk_add_f32 v[14:15], v[12:13], v[144:145]
	v_cvt_pk_bf16_f32 v12, v20, v21
	v_cvt_pk_bf16_f32 v13, v22, v23
	s_waitcnt vmcnt(6)
	v_lshlrev_b32_e32 v146, 16, v90
	v_and_b32_e32 v147, 0xffff0000, v90
	v_lshlrev_b32_e32 v90, 16, v91
	v_and_b32_e32 v91, 0xffff0000, v91
	v_lshlrev_b32_e32 v148, 16, v92
	v_and_b32_e32 v149, 0xffff0000, v92
	v_lshlrev_b32_e32 v92, 16, v93
	v_and_b32_e32 v93, 0xffff0000, v93
	v_cvt_pk_bf16_f32 v14, v14, v15
	v_cvt_pk_bf16_f32 v15, v24, v25
	global_store_dwordx4 v[28:29], v[12:15], off offset:256
	s_waitcnt vmcnt(6)
	v_lshlrev_b32_e32 v66, 16, v96
	v_and_b32_e32 v67, 0xffff0000, v96
	v_lshl_add_u64 v[12:13], s[24:25], 0, v[64:65]
	v_lshlrev_b32_e32 v96, 16, v97
	v_and_b32_e32 v97, 0xffff0000, v97
	v_pk_add_f32 v[14:15], v[18:19], v[90:91]
	v_pk_add_f32 v[16:17], v[16:17], v[146:147]
	v_pk_add_f32 v[18:19], v[10:11], v[92:93]
	v_pk_add_f32 v[10:11], v[8:9], v[148:149]
	v_cvt_pk_bf16_f32 v8, v16, v17
	v_cvt_pk_bf16_f32 v9, v14, v15
	v_lshl_add_u64 v[12:13], v[12:13], 0, v[120:121]
	v_lshlrev_b32_e32 v68, 16, v94
	v_and_b32_e32 v69, 0xffff0000, v94
	v_lshlrev_b32_e32 v94, 16, v95
	v_and_b32_e32 v95, 0xffff0000, v95
	v_cvt_pk_bf16_f32 v10, v10, v11
	v_cvt_pk_bf16_f32 v11, v18, v19
	global_store_dwordx4 v[12:13], v[8:11], off
	v_pk_add_f32 v[6:7], v[6:7], v[94:95]
	v_pk_add_f32 v[4:5], v[4:5], v[68:69]
	v_pk_add_f32 v[8:9], v[2:3], v[96:97]
	v_pk_add_f32 v[2:3], v[0:1], v[66:67]
	v_cvt_pk_bf16_f32 v0, v4, v5
	v_cvt_pk_bf16_f32 v1, v6, v7
	s_nop 0
	v_cvt_pk_bf16_f32 v2, v2, v3
	v_cvt_pk_bf16_f32 v3, v8, v9
	global_store_dwordx4 v[12:13], v[0:3], off offset:256
	s_cbranch_vccnz .LBB0_1283
	s_andn2_b64 vcc, exec, s[10:11]
	s_cbranch_vccnz .LBB0_1282
	s_barrier
	s_branch .LBB0_1282

; __device__ __forceinline__ float fexp2(float x) { return __builtin_amdgcn_exp2f(x); }
; __device__ __forceinline__ float frcp(float x) { return __builtin_amdgcn_rcpf(x); }
;     __device__ __forceinline__ void operator()(AccRef acc, const pg8::Unit& u, int wr, int wc, int, int) const {
;     ...
;             for (int m = 0; m < 4; ++m) { const int row = u.pm * 256 + ai * 128 + wr * 64 + m * 16 + fr;
; #pragma unroll
;                 for (int bj = 0; bj < 2; ++bj) { const size_t off = (size_t)row * DM + u.pn * 256 + bj * 128 + wc * 32 + 8 * fq; hwv[m][bj] = *(const v4u*)(HB + off); pwv[m][bj] = *(const v4u*)(XB + off); } }
;             asm volatile("" ::: "memory");
; #pragma unroll
;             for (int m = 0; m < 4; ++m) {
;                 const int row = u.pm * 256 + ai * 128 + wr * 64 + m * 16 + fr;
;                 float ss = 0.f;
; #pragma unroll
;                 for (int bj = 0; bj < 2; ++bj) {
;                     const int c0 = u.pn * 256 + bj * 128 + wc * 32 + 8 * fq;
;                     const v4u hw = hwv[m][bj], pw = pwv[m][bj];
;                     const float hh[8] = {bf_lo(hw.x), bf_hi(hw.x), bf_lo(hw.y), bf_hi(hw.y), bf_lo(hw.z), bf_hi(hw.z), bf_lo(hw.w), bf_hi(hw.w)};
;                     const float pp[8] = {bf_lo(pw.x), bf_hi(pw.x), bf_lo(pw.y), bf_hi(pw.y), bf_lo(pw.z), bf_hi(pw.z), bf_lo(pw.w), bf_hi(pw.w)};
;                     float o[8];
; #pragma unroll
;                     for (int j = 0; j < 4; ++j) {
;                         o[j] = hh[j] + pp[j] * frcp(1.0f + fexp2(-acc[ai][bj][m][0][j] * LOG2E));
;                         o[4 + j] = hh[4 + j] + pp[4 + j] * frcp(1.0f + fexp2(-acc[ai][bj][m][1][j] * LOG2E));
;                     }
.LBB0_1372:
	s_mov_b64 s[24:25], s[20:21]
	s_mov_b64 s[26:27], s[22:23]
	s_add_u32 s38, s24, 0x7800000
	s_addc_u32 s39, s25, 0
	s_add_u32 s26, s24, 0x3600000
	s_addc_u32 s27, s25, 0
	s_add_u32 s24, s24, 0x85000
	v_mov_b32_e32 v134, v196
	s_addc_u32 s25, s25, 0
	s_lshl_b32 s11, s36, 8
	s_add_i32 s11, s11, s35
	s_lshl_b32 s30, s30, 8
	v_ashrrev_i32_e32 v128, 1, v134
	v_and_or_b32 v190, v134, 15, s11
	s_ashr_i32 s31, s30, 31
	v_and_b32_e32 v128, -8, v128
	v_ashrrev_i32_e32 v129, 31, v128
	s_or_b64 s[50:51], s[30:31], s[28:29]
	v_ashrrev_i32_e32 v191, 31, v190
	v_lshl_add_u64 v[188:189], s[50:51], 0, v[128:129]
	v_lshlrev_b64 v[130:131], 10, v[190:191]
	v_lshl_add_u64 v[130:131], v[188:189], 0, v[130:131]
	v_lshlrev_b64 v[130:131], 1, v[130:131]
	v_lshl_add_u64 v[132:133], s[38:39], 0, v[130:131]
	v_lshl_add_u64 v[130:131], s[26:27], 0, v[130:131]
	global_load_dwordx4 v[204:207], v[132:133], off nt
	global_load_dwordx4 v[212:215], v[132:133], off offset:256 nt
	global_load_dwordx4 v[208:211], v[130:131], off nt
	global_load_dwordx4 v[216:219], v[130:131], off offset:256 nt
	v_mul_f32_e32 v124, 0xbfb8aa3b, v124
	v_exp_f32_e32 v124, v124
	v_mul_f32_e32 v120, 0xbfb8aa3b, v120
	v_exp_f32_e32 v120, v120
	v_mul_f32_e32 v125, 0xbfb8aa3b, v125
	v_add_f32_e32 v124, 1.0, v124
	v_rcp_f32_e32 v225, v124
	v_or_b32_e32 v194, 16, v190
	v_or_b32_e32 v192, 32, v190
	v_or_b32_e32 v124, 48, v190
	v_exp_f32_e32 v224, v125
	v_add_f32_e32 v120, 1.0, v120
	s_or_b32 s11, s30, s28
	v_ashrrev_i32_e32 v195, 31, v194
	v_ashrrev_i32_e32 v193, 31, v192
	v_ashrrev_i32_e32 v125, 31, v124
	v_cmp_gt_u32_e32 vcc, 16, v134
	v_rcp_f32_e32 v226, v120
	v_add_u32_e32 v120, s11, v128
	v_lshlrev_b64 v[128:129], 11, v[190:191]
	v_lshlrev_b64 v[134:135], 10, v[194:195]
	v_lshlrev_b64 v[136:137], 10, v[192:193]
	v_lshlrev_b64 v[138:139], 10, v[124:125]
	v_lshl_add_u64 v[220:221], s[26:27], 0, v[128:129]
	v_lshl_add_u64 v[128:129], v[134:135], 0, v[188:189]
	v_lshl_add_u64 v[134:135], v[136:137], 0, v[188:189]
	v_lshl_add_u64 v[136:137], v[138:139], 0, v[188:189]
	v_lshlrev_b64 v[128:129], 1, v[128:129]
	v_lshlrev_b64 v[134:135], 1, v[134:135]
	v_lshlrev_b64 v[132:133], 1, v[136:137]
	v_lshl_add_u64 v[130:131], s[38:39], 0, v[128:129]
	v_lshl_add_u64 v[128:129], s[26:27], 0, v[128:129]
	v_lshl_add_u64 v[136:137], s[38:39], 0, v[134:135]
	v_lshl_add_u64 v[134:135], s[26:27], 0, v[134:135]
	v_lshl_add_u64 v[138:139], s[38:39], 0, v[132:133]
	v_lshl_add_u64 v[222:223], s[26:27], 0, v[132:133]
	global_load_dwordx4 v[172:175], v[130:131], off nt
	global_load_dwordx4 v[164:167], v[130:131], off offset:256 nt
	global_load_dwordx4 v[168:171], v[128:129], off nt
	global_load_dwordx4 v[160:163], v[128:129], off offset:256 nt
	global_load_dwordx4 v[156:159], v[136:137], off nt
	global_load_dwordx4 v[148:151], v[136:137], off offset:256 nt
	global_load_dwordx4 v[152:155], v[134:135], off nt
	global_load_dwordx4 v[144:147], v[134:135], off offset:256 nt
	global_load_dwordx4 v[140:143], v[138:139], off nt
	s_nop 0
	global_load_dwordx4 v[132:135], v[138:139], off offset:256 nt
	s_nop 0
	global_load_dwordx4 v[136:139], v[222:223], off nt
	global_load_dwordx4 v[128:131], v[222:223], off offset:256 nt
	v_mul_f32_e32 v121, 0xbfb8aa3b, v121
	v_exp_f32_e32 v121, v121
	v_mul_f32_e32 v126, 0xbfb8aa3b, v126
	v_exp_f32_e32 v126, v126
	v_mul_f32_e32 v112, 0xbfb8aa3b, v112
	v_add_f32_e32 v121, 1.0, v121
	v_rcp_f32_e32 v121, v121
	v_exp_f32_e32 v112, v112
	v_mul_f32_e32 v122, 0xbfb8aa3b, v122
	v_mul_f32_e32 v123, 0xbfb8aa3b, v123
	v_exp_f32_e32 v122, v122
	v_exp_f32_e32 v123, v123
	v_add_f32_e32 v112, 1.0, v112
	v_mul_f32_e32 v113, 0xbfb8aa3b, v113
	v_rcp_f32_e32 v112, v112
	v_exp_f32_e32 v113, v113
	v_add_f32_e32 v224, 1.0, v224
	v_add_f32_e32 v122, 1.0, v122
	v_add_f32_e32 v123, 1.0, v123
	v_rcp_f32_e32 v224, v224
	v_rcp_f32_e32 v122, v122
	v_rcp_f32_e32 v123, v123
	v_mul_f32_e32 v114, 0xbfb8aa3b, v114
	v_exp_f32_e32 v114, v114
	v_mul_f32_e32 v116, 0xbfb8aa3b, v116
	v_exp_f32_e32 v116, v116
	v_mul_f32_e32 v117, 0xbfb8aa3b, v117
	v_exp_f32_e32 v117, v117
	v_mul_f32_e32 v115, 0xbfb8aa3b, v115
	v_add_f32_e32 v116, 1.0, v116
	v_rcp_f32_e32 v116, v116
	v_add_f32_e32 v117, 1.0, v117
	v_rcp_f32_e32 v117, v117
	v_exp_f32_e32 v115, v115
	s_waitcnt vmcnt(0)
; __device__ __forceinline__ unsigned cvt_pk(float lo, float hi) { unsigned r; asm("v_cvt_pk_bf16_f32 %0, %1, %2" : "=v"(r) : "v"(lo), "v"(hi)); return r; }
; __device__ __forceinline__ float fexp2(float x) { return __builtin_amdgcn_exp2f(x); }
; __device__ __forceinline__ float frcp(float x) { return __builtin_amdgcn_rcpf(x); }
;     __device__ __forceinline__ void operator()(AccRef acc, const pg8::Unit& u, int wr, int wc, int, int) const {
;     ...
;                     const v4u hw = hwv[m][bj], pw = pwv[m][bj];
;                     const float hh[8] = {bf_lo(hw.x), bf_hi(hw.x), bf_lo(hw.y), bf_hi(hw.y), bf_lo(hw.z), bf_hi(hw.z), bf_lo(hw.w), bf_hi(hw.w)};
;                     const float pp[8] = {bf_lo(pw.x), bf_hi(pw.x), bf_lo(pw.y), bf_hi(pw.y), bf_lo(pw.z), bf_hi(pw.z), bf_lo(pw.w), bf_hi(pw.w)};
;                     float o[8];
; #pragma unroll
;                     for (int j = 0; j < 4; ++j) {
;                         o[j] = hh[j] + pp[j] * frcp(1.0f + fexp2(-acc[ai][bj][m][0][j] * LOG2E));
;                         o[4 + j] = hh[4 + j] + pp[4 + j] * frcp(1.0f + fexp2(-acc[ai][bj][m][1][j] * LOG2E));
;                     }
;                     v4u w; w.x = cvt_pk(o[0], o[1]); w.y = cvt_pk(o[2], o[3]); w.z = cvt_pk(o[4], o[5]); w.w = cvt_pk(o[6], o[7]);
;                     *(v4u*)(XB + (size_t)row * DM + c0) = w;
; #pragma unroll
;                     for (int j = 0; j < 8; ++j) ss += o[j] * o[j];
;                 }
;                 ss += __shfl_xor(ss, 16); ss += __shfl_xor(ss, 32);
;                 if (fq == 0) __hip_atomic_fetch_add(ssq + row, ss, __ATOMIC_RELAXED, __HIP_MEMORY_SCOPE_AGENT);
	v_lshlrev_b32_e32 v229, 16, v206
	v_and_b32_e32 v230, 0xffff0000, v206
	v_lshlrev_b32_e32 v231, 16, v207
	v_and_b32_e32 v232, 0xffff0000, v207
	v_lshlrev_b32_e32 v206, 16, v209
	v_and_b32_e32 v207, 0xffff0000, v209
	v_and_b32_e32 v209, 0xffff0000, v210
	v_fmac_f32_e32 v230, v121, v209
	v_add_f32_e32 v121, 1.0, v126
	v_mul_f32_e32 v126, 0xbfb8aa3b, v127
	v_rcp_f32_e32 v121, v121
	v_exp_f32_e32 v126, v126
	v_lshlrev_b32_e32 v222, 16, v204
	v_and_b32_e32 v223, 0xffff0000, v204
	v_lshlrev_b32_e32 v227, 16, v205
	v_and_b32_e32 v228, 0xffff0000, v205
	v_lshlrev_b32_e32 v204, 16, v208
	v_and_b32_e32 v205, 0xffff0000, v208
	v_lshlrev_b32_e32 v208, 16, v210
	v_fmac_f32_e32 v229, v226, v208
	v_add_f32_e32 v126, 1.0, v126
	v_fmac_f32_e32 v227, v121, v206
	v_lshlrev_b32_e32 v127, 16, v213
	v_and_b32_e32 v208, 0xffff0000, v213
	v_lshlrev_b32_e32 v209, 16, v214
	v_lshlrev_b32_e32 v121, 16, v216
	v_and_b32_e32 v213, 0xffff0000, v216
	v_lshlrev_b32_e32 v216, 16, v218
	v_rcp_f32_e32 v126, v126
	v_fmac_f32_e32 v209, v112, v216
	v_add_f32_e32 v112, 1.0, v113
	v_mul_f32_e32 v113, 0xbfb8aa3b, v118
	v_rcp_f32_e32 v112, v112
	v_exp_f32_e32 v113, v113
	v_lshlrev_b32_e32 v210, 16, v211
	v_and_b32_e32 v211, 0xffff0000, v211
	v_fmac_f32_e32 v223, v224, v205
	v_fmac_f32_e32 v231, v122, v210
	v_fmac_f32_e32 v228, v126, v207
	v_fmac_f32_e32 v232, v123, v211
	v_lshlrev_b32_e32 v123, 16, v212
	v_and_b32_e32 v126, 0xffff0000, v212
	v_and_b32_e32 v210, 0xffff0000, v214
	v_lshlrev_b32_e32 v211, 16, v215
	v_and_b32_e32 v212, 0xffff0000, v215
	v_lshlrev_b32_e32 v214, 16, v217
	v_and_b32_e32 v215, 0xffff0000, v217
	v_and_b32_e32 v217, 0xffff0000, v218
	v_fmac_f32_e32 v222, v225, v204
	v_mul_f32_e32 v122, v223, v223
	v_fmac_f32_e32 v210, v112, v217
	v_add_f32_e32 v112, 1.0, v113
	v_add_f32_e32 v113, 1.0, v114
	v_mul_f32_e32 v114, 0xbfb8aa3b, v119
	v_fmac_f32_e32 v122, v222, v222
	v_exp_f32_e32 v114, v114
	v_fmac_f32_e32 v122, v227, v227
	v_fmac_f32_e32 v122, v228, v228
	v_fmac_f32_e32 v122, v229, v229
	v_fmac_f32_e32 v122, v230, v230
	v_rcp_f32_e32 v112, v112
	v_add_f32_e32 v114, 1.0, v114
	v_fmac_f32_e32 v122, v231, v231
	v_rcp_f32_e32 v114, v114
	v_fmac_f32_e32 v122, v232, v232
	v_fmac_f32_e32 v123, v116, v121
	v_fmac_f32_e32 v126, v117, v213
	v_fmac_f32_e32 v122, v123, v123
	v_rcp_f32_e32 v113, v113
	v_add_f32_e32 v115, 1.0, v115
	v_fmac_f32_e32 v127, v112, v214
	v_fmac_f32_e32 v122, v126, v126
	v_rcp_f32_e32 v115, v115
	v_fmac_f32_e32 v208, v114, v215
	v_fmac_f32_e32 v122, v127, v127
	v_fmac_f32_e32 v122, v208, v208
	v_lshlrev_b32_e32 v218, 16, v219
	v_fmac_f32_e32 v122, v209, v209
	v_and_b32_e32 v219, 0xffff0000, v219
	v_fmac_f32_e32 v211, v113, v218
	v_fmac_f32_e32 v122, v210, v210
	v_fmac_f32_e32 v212, v115, v219
	v_fmac_f32_e32 v122, v211, v211
	v_fmac_f32_e32 v122, v212, v212
	ds_bpermute_b32 v112, v197, v122
	v_ashrrev_i32_e32 v121, 31, v120
	v_lshl_add_u64 v[118:119], v[120:121], 1, v[220:221]
	v_cvt_pk_bf16_f32 v204, v222, v223
	v_cvt_pk_bf16_f32 v205, v227, v228
	s_waitcnt lgkmcnt(0)
	v_add_f32_e32 v112, v122, v112
	ds_bpermute_b32 v113, v198, v112
	v_cvt_pk_bf16_f32 v206, v229, v230
	v_cvt_pk_bf16_f32 v207, v231, v232
	global_store_dwordx4 v[118:119], v[204:207], off
	v_cvt_pk_bf16_f32 v114, v123, v126
	v_cvt_pk_bf16_f32 v115, v127, v208
	v_cvt_pk_bf16_f32 v116, v209, v210
	v_cvt_pk_bf16_f32 v117, v211, v212
	global_store_dwordx4 v[118:119], v[114:117], off offset:256
	s_and_saveexec_b64 s[30:31], vcc
	s_cbranch_execz .LBB0_1374
	s_waitcnt lgkmcnt(0)
	v_add_f32_e32 v114, v112, v113
	v_lshl_add_u64 v[112:113], v[190:191], 2, s[24:25]
	global_atomic_add_f32 v[112:113], v114, off

; __device__ __forceinline__ unsigned cvt_pk(float lo, float hi) { unsigned r; asm("v_cvt_pk_bf16_f32 %0, %1, %2" : "=v"(r) : "v"(lo), "v"(hi)); return r; }
; __device__ __forceinline__ float fexp2(float x) { return __builtin_amdgcn_exp2f(x); }
; __device__ __forceinline__ float frcp(float x) { return __builtin_amdgcn_rcpf(x); }
;     __device__ __forceinline__ void operator()(AccRef acc, const pg8::Unit& u, int wr, int wc, int, int) const {
;     ...
;             for (int m = 0; m < 4; ++m) { const int row = u.pm * 256 + ai * 128 + wr * 64 + m * 16 + fr;
; #pragma unroll
;                 for (int bj = 0; bj < 2; ++bj) { const size_t off = (size_t)row * DM + u.pn * 256 + bj * 128 + wc * 32 + 8 * fq; hwv[m][bj] = *(const v4u*)(HB + off); pwv[m][bj] = *(const v4u*)(XB + off); } }
;             asm volatile("" ::: "memory");
; #pragma unroll
;             for (int m = 0; m < 4; ++m) {
;                 const int row = u.pm * 256 + ai * 128 + wr * 64 + m * 16 + fr;
;                 float ss = 0.f;
; #pragma unroll
;                 for (int bj = 0; bj < 2; ++bj) {
;                     const int c0 = u.pn * 256 + bj * 128 + wc * 32 + 8 * fq;
;                     const v4u hw = hwv[m][bj], pw = pwv[m][bj];
;                     const float hh[8] = {bf_lo(hw.x), bf_hi(hw.x), bf_lo(hw.y), bf_hi(hw.y), bf_lo(hw.z), bf_hi(hw.z), bf_lo(hw.w), bf_hi(hw.w)};
;                     const float pp[8] = {bf_lo(pw.x), bf_hi(pw.x), bf_lo(pw.y), bf_hi(pw.y), bf_lo(pw.z), bf_hi(pw.z), bf_lo(pw.w), bf_hi(pw.w)};
;                     float o[8];
; #pragma unroll
;                     for (int j = 0; j < 4; ++j) {
;                         o[j] = hh[j] + pp[j] * frcp(1.0f + fexp2(-acc[ai][bj][m][0][j] * LOG2E));
;                         o[4 + j] = hh[4 + j] + pp[4 + j] * frcp(1.0f + fexp2(-acc[ai][bj][m][1][j] * LOG2E));
;                     }
;                     v4u w; w.x = cvt_pk(o[0], o[1]); w.y = cvt_pk(o[2], o[3]); w.z = cvt_pk(o[4], o[5]); w.w = cvt_pk(o[6], o[7]);
;                     *(v4u*)(XB + (size_t)row * DM + c0) = w;
; #pragma unroll
;                     for (int j = 0; j < 8; ++j) ss += o[j] * o[j];
;                 }
;                 ss += __shfl_xor(ss, 16); ss += __shfl_xor(ss, 32);
;                 if (fq == 0) __hip_atomic_fetch_add(ssq + row, ss, __ATOMIC_RELAXED, __HIP_MEMORY_SCOPE_AGENT);
.LBB0_1380:
	s_or_b64 exec, exec, s[30:31]
	v_add_u32_e32 v118, 0x80, v190
	v_ashrrev_i32_e32 v119, 31, v118
	s_waitcnt lgkmcnt(0)
	v_lshlrev_b64 v[64:65], 10, v[118:119]
	v_lshl_add_u64 v[64:65], v[64:65], 0, v[188:189]
	v_lshlrev_b64 v[64:65], 1, v[64:65]
	v_lshl_add_u64 v[66:67], s[38:39], 0, v[64:65]
	v_lshl_add_u64 v[64:65], s[26:27], 0, v[64:65]
	global_load_dwordx4 v[122:125], v[66:67], off nt
	global_load_dwordx4 v[130:133], v[66:67], off offset:256 nt
	global_load_dwordx4 v[126:129], v[64:65], off nt
	global_load_dwordx4 v[134:137], v[64:65], off offset:256 nt
	v_add_u32_e32 v116, 0x90, v190
	v_add_u32_e32 v114, 0xa0, v190
	v_add_u32_e32 v112, 0xb0, v190
	v_mul_f32_e32 v60, 0xbfb8aa3b, v60
	v_mul_f32_e32 v56, 0xbfb8aa3b, v56
	v_mul_f32_e32 v61, 0xbfb8aa3b, v61
	v_mul_f32_e32 v57, 0xbfb8aa3b, v57
	v_ashrrev_i32_e32 v117, 31, v116
	v_ashrrev_i32_e32 v115, 31, v114
	v_ashrrev_i32_e32 v113, 31, v112
	v_exp_f32_e32 v72, v60
	v_exp_f32_e32 v73, v56
	v_exp_f32_e32 v74, v61
	v_exp_f32_e32 v75, v57
	v_lshlrev_b64 v[56:57], 10, v[116:117]
	v_lshlrev_b64 v[60:61], 10, v[114:115]
	v_lshlrev_b64 v[68:69], 10, v[112:113]
	v_lshl_add_u64 v[56:57], v[56:57], 0, v[188:189]
	v_lshl_add_u64 v[60:61], v[60:61], 0, v[188:189]
	v_lshl_add_u64 v[68:69], v[68:69], 0, v[188:189]
	v_lshlrev_b64 v[70:71], 11, v[118:119]
	v_lshlrev_b64 v[56:57], 1, v[56:57]
	v_lshlrev_b64 v[60:61], 1, v[60:61]
	v_lshlrev_b64 v[66:67], 1, v[68:69]
	v_lshl_add_u64 v[138:139], s[26:27], 0, v[70:71]
	v_lshl_add_u64 v[68:69], s[38:39], 0, v[56:57]
	v_lshl_add_u64 v[70:71], s[38:39], 0, v[60:61]
	v_lshl_add_u64 v[64:65], s[38:39], 0, v[66:67]
	v_lshl_add_u64 v[66:67], s[26:27], 0, v[66:67]
	v_lshl_add_u64 v[56:57], s[26:27], 0, v[56:57]
	v_lshl_add_u64 v[60:61], s[26:27], 0, v[60:61]
	v_add_f32_e32 v140, 1.0, v72
	v_add_f32_e32 v141, 1.0, v73
	v_add_f32_e32 v142, 1.0, v74
	v_add_f32_e32 v143, 1.0, v75
	global_load_dwordx4 v[108:111], v[68:69], off nt
	global_load_dwordx4 v[100:103], v[68:69], off offset:256 nt
	global_load_dwordx4 v[104:107], v[56:57], off nt
	global_load_dwordx4 v[96:99], v[56:57], off offset:256 nt
	global_load_dwordx4 v[92:95], v[70:71], off nt
	global_load_dwordx4 v[84:87], v[70:71], off offset:256 nt
	global_load_dwordx4 v[88:91], v[60:61], off nt
	global_load_dwordx4 v[80:83], v[60:61], off offset:256 nt
	global_load_dwordx4 v[76:79], v[64:65], off nt
	s_nop 0
	global_load_dwordx4 v[68:71], v[64:65], off offset:256 nt
	global_load_dwordx4 v[72:75], v[66:67], off nt
	s_nop 0
	global_load_dwordx4 v[64:67], v[66:67], off offset:256 nt
	v_mul_f32_e32 v58, 0xbfb8aa3b, v58
	v_exp_f32_e32 v58, v58
	v_rcp_f32_e32 v57, v141
	v_mul_f32_e32 v62, 0xbfb8aa3b, v62
	v_rcp_f32_e32 v60, v142
	v_exp_f32_e32 v62, v62
	v_rcp_f32_e32 v56, v140
	v_mul_f32_e32 v48, 0xbfb8aa3b, v48
	v_exp_f32_e32 v48, v48
	v_add_f32_e32 v62, 1.0, v62
	v_mul_f32_e32 v49, 0xbfb8aa3b, v49
	v_exp_f32_e32 v49, v49
	v_add_f32_e32 v48, 1.0, v48
	v_rcp_f32_e32 v48, v48
	v_rcp_f32_e32 v61, v143
	v_mul_f32_e32 v50, 0xbfb8aa3b, v50
	v_mul_f32_e32 v59, 0xbfb8aa3b, v59
	v_exp_f32_e32 v50, v50
	v_exp_f32_e32 v59, v59
	v_mul_f32_e32 v52, 0xbfb8aa3b, v52
	v_exp_f32_e32 v52, v52
	v_mul_f32_e32 v53, 0xbfb8aa3b, v53
	v_exp_f32_e32 v53, v53
	v_add_f32_e32 v59, 1.0, v59
	v_rcp_f32_e32 v59, v59
	v_add_f32_e32 v52, 1.0, v52
	v_rcp_f32_e32 v52, v52
	v_add_f32_e32 v53, 1.0, v53
	v_rcp_f32_e32 v53, v53
	v_mul_f32_e32 v51, 0xbfb8aa3b, v51
	v_exp_f32_e32 v51, v51
	s_waitcnt vmcnt(15)
	v_lshlrev_b32_e32 v142, 16, v124
	v_lshlrev_b32_e32 v140, 16, v122
	s_waitcnt vmcnt(13)
	v_lshlrev_b32_e32 v146, 16, v128
	v_fmac_f32_e32 v142, v57, v146
	v_add_f32_e32 v57, 1.0, v58
	v_mul_f32_e32 v58, 0xbfb8aa3b, v63
	v_exp_f32_e32 v58, v58
	v_lshlrev_b32_e32 v144, 16, v126
	v_fmac_f32_e32 v140, v56, v144
	v_rcp_f32_e32 v56, v62
	v_add_f32_e32 v58, 1.0, v58
	v_and_b32_e32 v122, 0xffff0000, v122
	v_and_b32_e32 v126, 0xffff0000, v126
	v_rcp_f32_e32 v58, v58
	v_fmac_f32_e32 v122, v60, v126
	v_rcp_f32_e32 v57, v57
	v_lshlrev_b32_e32 v141, 16, v123
	v_lshlrev_b32_e32 v145, 16, v127
	v_mul_f32_e32 v60, v122, v122
	v_and_b32_e32 v123, 0xffff0000, v123
	v_and_b32_e32 v127, 0xffff0000, v127
	v_fmac_f32_e32 v141, v56, v145
	v_fmac_f32_e32 v60, v140, v140
	v_lshlrev_b32_e32 v143, 16, v125
	v_lshlrev_b32_e32 v147, 16, v129
	v_fmac_f32_e32 v123, v58, v127
	v_fmac_f32_e32 v60, v141, v141
	v_fmac_f32_e32 v143, v57, v147
	v_cvt_pk_bf16_f32 v56, v140, v122
	v_cvt_pk_bf16_f32 v57, v141, v123
	v_fmac_f32_e32 v60, v123, v123
	v_lshlrev_b32_e32 v63, 16, v131
	v_and_b32_e32 v122, 0xffff0000, v131
	v_lshlrev_b32_e32 v123, 16, v132
	s_waitcnt vmcnt(12)
	v_lshlrev_b32_e32 v131, 16, v136
	v_fmac_f32_e32 v123, v48, v131
	v_add_f32_e32 v48, 1.0, v49
	v_mul_f32_e32 v49, 0xbfb8aa3b, v54
	v_rcp_f32_e32 v48, v48
	v_exp_f32_e32 v49, v49
	v_and_b32_e32 v124, 0xffff0000, v124
	v_and_b32_e32 v128, 0xffff0000, v128
	v_fmac_f32_e32 v124, v61, v128
	v_fmac_f32_e32 v60, v142, v142
	v_cvt_pk_bf16_f32 v58, v142, v124
	v_fmac_f32_e32 v60, v124, v124
	v_and_b32_e32 v124, 0xffff0000, v132
	v_and_b32_e32 v132, 0xffff0000, v136
	v_fmac_f32_e32 v124, v48, v132
	v_add_f32_e32 v48, 1.0, v49
	v_add_f32_e32 v49, 1.0, v50
	v_mul_f32_e32 v50, 0xbfb8aa3b, v55
	v_exp_f32_e32 v50, v50
	v_and_b32_e32 v125, 0xffff0000, v125
	v_and_b32_e32 v129, 0xffff0000, v129
	v_rcp_f32_e32 v48, v48
	v_add_f32_e32 v50, 1.0, v50
	v_fmac_f32_e32 v125, v59, v129
	v_fmac_f32_e32 v60, v143, v143
	v_lshlrev_b32_e32 v61, 16, v130
	v_lshlrev_b32_e32 v59, 16, v134
	v_rcp_f32_e32 v50, v50
	v_fmac_f32_e32 v60, v125, v125
	v_and_b32_e32 v62, 0xffff0000, v130
	v_and_b32_e32 v128, 0xffff0000, v134
	v_fmac_f32_e32 v61, v52, v59
	v_lshlrev_b32_e32 v129, 16, v135
	v_fmac_f32_e32 v62, v53, v128
	v_fmac_f32_e32 v60, v61, v61
	v_and_b32_e32 v130, 0xffff0000, v135
	v_rcp_f32_e32 v49, v49
	v_add_f32_e32 v51, 1.0, v51
	v_fmac_f32_e32 v63, v48, v129
	v_fmac_f32_e32 v60, v62, v62
	v_rcp_f32_e32 v51, v51
	v_fmac_f32_e32 v122, v50, v130
	v_fmac_f32_e32 v60, v63, v63
	v_fmac_f32_e32 v60, v122, v122
	v_lshlrev_b32_e32 v126, 16, v133
	v_and_b32_e32 v127, 0xffff0000, v133
	v_lshlrev_b32_e32 v133, 16, v137
	v_fmac_f32_e32 v60, v123, v123
	v_and_b32_e32 v134, 0xffff0000, v137
	v_fmac_f32_e32 v126, v49, v133
	v_fmac_f32_e32 v60, v124, v124
	v_fmac_f32_e32 v127, v51, v134
	v_fmac_f32_e32 v60, v126, v126
	v_fmac_f32_e32 v60, v127, v127
	ds_bpermute_b32 v48, v197, v60
	v_lshl_add_u64 v[54:55], v[120:121], 1, v[138:139]
	v_cvt_pk_bf16_f32 v59, v143, v125
	global_store_dwordx4 v[54:55], v[56:59], off
	v_cvt_pk_bf16_f32 v50, v61, v62
	s_waitcnt lgkmcnt(0)
	v_add_f32_e32 v48, v60, v48
	ds_bpermute_b32 v49, v198, v48
	v_cvt_pk_bf16_f32 v51, v63, v122
	v_cvt_pk_bf16_f32 v52, v123, v124
	v_cvt_pk_bf16_f32 v53, v126, v127
	global_store_dwordx4 v[54:55], v[50:53], off offset:256
	s_and_saveexec_b64 s[30:31], vcc
	s_cbranch_execz .LBB0_1382
	s_waitcnt lgkmcnt(0)
	v_add_f32_e32 v50, v48, v49
	v_lshl_add_u64 v[48:49], v[118:119], 2, s[24:25]
	global_atomic_add_f32 v[48:49], v50, off
